# FF1 phases: 6 of 8 epilogue stores per tile deferred into next tile's K-loop load segments (data kept in 24 spare VGPRs)
# baseline (speedup 1.0000x reference)
; #define PG8_STAGE(bufoff, gbase, voff) do { _Pragma("unroll") for (int _i = 0; _i < 2; ++_i) \
;         __builtin_amdgcn_global_load_lds((const unsigned*)((const char*)(gbase) + (voff)[_i]), (PG8_LAS unsigned*)(lds + (bufoff) + ldsw + _i * 8192), 16, 0, 0); } while (0)
; #define PG8_WAIT_V(n) asm volatile("s_waitcnt vmcnt(" #n ")" ::: "memory")
; #define PG8_BAR __builtin_amdgcn_s_barrier()
; template <class Epi, class Sched, bool ALIGN_EPI = false, bool SP2 = false>
; __device__ __forceinline__ void gemm_phase(PG8_LAS unsigned char* lds, const Gemm g, const Sched& S, const Epi& E) {
;     ...
;     const unsigned ldsw = (unsigned)wid * 1024u;
;     const int aoff = lds_byte(wr * 64 + fr, fq * 8), boff = lds_byte(wc * 32 + fr, fq * 8);
;     ...
;         PG8_WAIT_V(2); PG8_BAR;
;         PG8_STAGE(PG8_SB(1, 0), cB + kstep, voffB); PG8_STAGE(PG8_SA(1, 0), cA + kstep, voffA); PG8_STAGE(PG8_SB(1, 1), cB + hstep + kstep, voffB);
;         PG8_WAIT_V(6); PG8_BAR;
.LBB0_708:
	s_add_u32 s8, s28, 0xfa00000
	s_addc_u32 s9, s29, 0
	s_lshl_b32 s10, s10, 5
	s_and_b32 s22, s10, 0x60
	s_mov_b64 s[10:11], 0x80
	s_add_i32 m0, s39, 0x18000
	v_lshl_add_u64 v[6:7], v[6:7], 0, s[10:11]
	s_ashr_i32 s59, s3, 31
	s_lshl_b32 s13, s12, 13
	s_lshl_b32 s23, s22, 7
	s_waitcnt vmcnt(2)
	s_barrier
	global_load_lds_dwordx4 v[6:7], off
	v_lshl_add_u64 v[4:5], v[4:5], 0, s[10:11]
	s_add_i32 m0, s39, 0x1a000
	s_add_i32 s60, s39, 0x8000
	s_add_i32 s61, s39, 0xa000
	global_load_lds_dwordx4 v[4:5], off
	v_lshl_add_u64 v[0:1], v[0:1], 0, s[10:11]
	s_mov_b32 m0, s60
	s_add_u32 s20, s42, 0x40080
	global_load_lds_dwordx4 v[0:1], off
	v_lshl_add_u64 v[0:1], v[2:3], 0, s[10:11]
	s_mov_b32 m0, s61
	s_addc_u32 s21, s43, 0
	global_load_lds_dwordx4 v[0:1], off
	s_add_i32 m0, s39, 0x1c000
	v_lshl_add_u64 v[0:1], s[20:21], 0, v[130:131]
	global_load_lds_dwordx4 v[0:1], off
	v_lshl_add_u64 v[0:1], s[20:21], 0, v[134:135]
	s_add_i32 m0, s39, 0x1e000
	s_sext_i32_i16 s71, s0
	global_load_lds_dwordx4 v[0:1], off
	v_and_b32_e32 v0, 15, v152
	v_lshlrev_b32_e32 v1, 1, v11
	v_lshlrev_b32_e32 v2, 6, v152
	s_movk_i32 s0, 0x3c0
	v_lshlrev_b32_e32 v3, 2, v152
	v_and_or_b32 v2, v2, s0, v1
	v_and_b32_e32 v3, 32, v3
	v_lshl_or_b32 v144, s12, 6, v0
	v_lshl_or_b32 v0, v0, 6, v1
	v_lshlrev_b32_e32 v1, 8, v152
	v_bitop3_b32 v145, s23, v2, v3 bitop3:0xf6
	v_and_b32_e32 v1, 0x38000, v1
	v_lshlrev_b32_e32 v2, 11, v10
	v_or3_b32 v1, v8, v1, v2
	s_waitcnt vmcnt(0)
	v_add_u32_e32 v136, v1, v9
	v_lshlrev_b32_e32 v1, 4, v12
	s_waitcnt vmcnt(6)
	s_cmpk_lt_u32 s1, 0x100
	v_and_b32_e32 v1, 0x78000, v1
	v_bitop3_b32 v0, v0, s13, v3 bitop3:0xde
	s_cselect_b64 s[12:13], -1, 0
	v_or3_b32 v1, v8, v1, v2
	s_add_i32 s62, 0, 0x10000
	s_add_i32 s63, 0, 0x14000
	v_or_b32_e32 v146, s22, v11
	v_mov_b32_e32 v137, v131
	v_add_u32_e32 v138, v1, v9
	v_mov_b32_e32 v139, v131
	v_mov_b64_e32 v[140:141], 0x1600
	v_mov_b64_e32 v[142:143], 0x15ff
	v_add_u32_e32 v147, s62, v145
	v_add_u32_e32 v148, s63, v145
	v_add_u32_e32 v149, 0, v0
	s_movk_i32 s70, 0x1600
	s_barrier
	s_mov_b32 s77, 6
	s_branch .LBB0_711

; #define PG8_STAGE(bufoff, gbase, voff) do { _Pragma("unroll") for (int _i = 0; _i < 2; ++_i) \
;         __builtin_amdgcn_global_load_lds((const unsigned*)((const char*)(gbase) + (voff)[_i]), (PG8_LAS unsigned*)(lds + (bufoff) + ldsw + _i * 8192), 16, 0, 0); } while (0)
; #define PG8_LDA(dst, b, h) do { _Pragma("unroll") for (int m = 0; m < 4; ++m) _Pragma("unroll") for (int k = 0; k < 2; ++k) dst[m][k] = *(const PG8_LAS bf16x8*)(lds + PG8_SA(b, h) + aoff + m * 2048 + k * 1024); } while (0)
; #define PG8_LDB(dst, b, h) do { _Pragma("unroll") for (int n = 0; n < 2; ++n) _Pragma("unroll") for (int k = 0; k < 2; ++k) dst[n][k] = *(const PG8_LAS bf16x8*)(lds + PG8_SB(b, h) + boff + n * 2048 + k * 1024); } while (0)
; #define PG8_MMA(ai, bj, At, Bt) do { __builtin_amdgcn_s_setprio(1); _Pragma("unroll") for (int m = 0; m < 4; ++m) _Pragma("unroll") for (int n = 0; n < 2; ++n) _Pragma("unroll") for (int k = 0; k < 2; ++k) \
;         acc[ai][bj][m][n] = __builtin_amdgcn_mfma_f32_16x16x32_bf16(Bt[n][k], At[m][k], acc[ai][bj][m][n], 0, 0, 0); __builtin_amdgcn_s_setprio(0); } while (0)
; #define PG8_WAIT_V(n) asm volatile("s_waitcnt vmcnt(" #n ")" ::: "memory")
; #define PG8_WAIT_L(n) asm volatile("s_waitcnt lgkmcnt(" #n ")" ::: "memory")
; #define PG8_BAR __builtin_amdgcn_s_barrier()
; #define PG8_SCHED __builtin_amdgcn_sched_barrier(0)
; template <class Epi, class Sched, bool ALIGN_EPI = false, bool SP2 = false>
; __device__ __forceinline__ void gemm_phase(PG8_LAS unsigned char* lds, const Gemm g, const Sched& S, const Epi& E) {
;     ...
;             PG8_LDB(B0, 0, 0); PG8_LDB(B1, 0, 1); PG8_SCHED; PG8_LDA(At, 0, 0); PG8_STAGE(PG8_SA(1, 1), a1 + hstep, voffA);
;             PG8_WAIT_V(8); PG8_WAIT_L(0); PG8_BAR; PG8_MMA(0, 0, At, B0); PG8_MMA(0, 1, At, B1); PG8_BAR; PG8_SCHED;
;             PG8_LDA(At, 0, 1); PG8_STAGE(PG8_SB(0, 0), b2, voffB); PG8_STAGE(PG8_SB(0, 1), b2 + hstep, voffB); PG8_STAGE(PG8_SA(0, 0), a2, voffA);
.LBB0_714:
	ds_read_b128 v[154:157], v147
	ds_read_b128 v[158:161], v147 offset:1024
	ds_read_b128 v[162:165], v147 offset:2048
	ds_read_b128 v[166:169], v147 offset:3072
	ds_read_b128 v[170:173], v148
	ds_read_b128 v[174:177], v148 offset:1024
	ds_read_b128 v[178:181], v148 offset:2048
	ds_read_b128 v[182:185], v148 offset:3072
	s_add_u32 s33, s40, 0xfffc0080
	s_addc_u32 s34, s41, -1
	s_cmp_eq_u32 s76, 12
	s_cselect_b32 s45, s23, s34
	s_cselect_b32 s44, s72, s33
	s_cselect_b32 s43, s21, s75
	s_cselect_b32 s42, s73, s74
	v_lshl_add_u64 v[150:151], s[40:41], 0, v[136:137]
	s_add_i32 m0, s39, 0xc000
	ds_read_b128 v[186:189], v149
	ds_read_b128 v[190:193], v149 offset:1024
	ds_read_b128 v[194:197], v149 offset:2048
	ds_read_b128 v[198:201], v149 offset:3072
	ds_read_b128 v[202:205], v149 offset:4096
	ds_read_b128 v[206:209], v149 offset:5120
	ds_read_b128 v[210:213], v149 offset:6144
	ds_read_b128 v[214:217], v149 offset:7168
	global_load_lds_dwordx4 v[150:151], off
	v_lshl_add_u64 v[150:151], s[40:41], 0, v[138:139]
	s_add_i32 m0, s39, 0xe000
	s_nop 0
	global_load_lds_dwordx4 v[150:151], off
	s_cmp_eq_u32 s77, 0
	s_cbranch_scc1 .Lds7_0_a
	s_cmp_eq_u32 s77, 4
	s_cbranch_scc1 .Lds7_0_b
.Lds7_0_ret:
	s_waitcnt vmcnt(8)
	s_waitcnt lgkmcnt(0)
	s_barrier
	s_setprio 1
	s_waitcnt lgkmcnt(0)
	v_mfma_f32_16x16x32_bf16 v[124:127], v[154:157], v[186:189], v[124:127]
	v_mfma_f32_16x16x32_bf16 v[116:119], v[162:165], v[186:189], v[116:119]
	v_mfma_f32_16x16x32_bf16 v[108:111], v[154:157], v[194:197], v[108:111]
	v_mfma_f32_16x16x32_bf16 v[100:103], v[162:165], v[194:197], v[100:103]
	v_mfma_f32_16x16x32_bf16 v[92:95], v[154:157], v[202:205], v[92:95]
	v_mfma_f32_16x16x32_bf16 v[84:87], v[162:165], v[202:205], v[84:87]
	v_mfma_f32_16x16x32_bf16 v[76:79], v[154:157], v[210:213], v[76:79]
	v_mfma_f32_16x16x32_bf16 v[68:71], v[162:165], v[210:213], v[68:71]
	v_mfma_f32_16x16x32_bf16 v[124:127], v[158:161], v[190:193], v[124:127]
	v_mfma_f32_16x16x32_bf16 v[116:119], v[166:169], v[190:193], v[116:119]
	v_mfma_f32_16x16x32_bf16 v[108:111], v[158:161], v[198:201], v[108:111]
	v_mfma_f32_16x16x32_bf16 v[100:103], v[166:169], v[198:201], v[100:103]
	v_mfma_f32_16x16x32_bf16 v[92:95], v[158:161], v[206:209], v[92:95]
	v_mfma_f32_16x16x32_bf16 v[84:87], v[166:169], v[206:209], v[84:87]
	v_mfma_f32_16x16x32_bf16 v[76:79], v[158:161], v[214:217], v[76:79]
	v_mfma_f32_16x16x32_bf16 v[68:71], v[166:169], v[214:217], v[68:71]
	s_setprio 0
	s_setprio 1
	v_mfma_f32_16x16x32_bf16 v[120:123], v[170:173], v[186:189], v[120:123]
	v_mfma_f32_16x16x32_bf16 v[112:115], v[178:181], v[186:189], v[112:115]
	v_mfma_f32_16x16x32_bf16 v[104:107], v[170:173], v[194:197], v[104:107]
	v_mfma_f32_16x16x32_bf16 v[96:99], v[178:181], v[194:197], v[96:99]
	v_mfma_f32_16x16x32_bf16 v[88:91], v[170:173], v[202:205], v[88:91]
	v_mfma_f32_16x16x32_bf16 v[80:83], v[178:181], v[202:205], v[80:83]
	v_mfma_f32_16x16x32_bf16 v[72:75], v[170:173], v[210:213], v[72:75]
	v_mfma_f32_16x16x32_bf16 v[64:67], v[178:181], v[210:213], v[64:67]
	v_mfma_f32_16x16x32_bf16 v[120:123], v[174:177], v[190:193], v[120:123]
	v_mfma_f32_16x16x32_bf16 v[112:115], v[182:185], v[190:193], v[112:115]
	v_mfma_f32_16x16x32_bf16 v[104:107], v[174:177], v[198:201], v[104:107]
	v_mfma_f32_16x16x32_bf16 v[96:99], v[182:185], v[198:201], v[96:99]
	v_mfma_f32_16x16x32_bf16 v[88:91], v[174:177], v[206:209], v[88:91]
	v_mfma_f32_16x16x32_bf16 v[80:83], v[182:185], v[206:209], v[80:83]
	v_mfma_f32_16x16x32_bf16 v[72:75], v[174:177], v[214:217], v[72:75]
	v_mfma_f32_16x16x32_bf16 v[64:67], v[182:185], v[214:217], v[64:67]
	s_setprio 0
	s_barrier
	s_add_i32 s33, s62, s52
	v_lshl_add_u64 v[150:151], s[42:43], 0, v[130:131]
	s_mov_b32 m0, s33
	ds_read_b128 v[186:189], v149 offset:16384
	ds_read_b128 v[190:193], v149 offset:17408
	ds_read_b128 v[194:197], v149 offset:18432
	ds_read_b128 v[198:201], v149 offset:19456
	ds_read_b128 v[202:205], v149 offset:20480
	ds_read_b128 v[206:209], v149 offset:21504
	ds_read_b128 v[210:213], v149 offset:22528
	ds_read_b128 v[214:217], v149 offset:23552
	global_load_lds_dwordx4 v[150:151], off
	s_add_i32 m0, s33, 0x2000
	s_add_u32 s78, s42, 0x40000
	v_lshl_add_u64 v[218:219], s[42:43], 0, v[134:135]
	s_addc_u32 s79, s43, 0
	s_add_i32 s33, s63, s52
	global_load_lds_dwordx4 v[218:219], off
	v_lshl_add_u64 v[220:221], s[78:79], 0, v[130:131]
	s_mov_b32 m0, s33
	v_lshl_add_u64 v[222:223], s[44:45], 0, v[132:133]
	global_load_lds_dwordx4 v[220:221], off
	v_lshl_add_u64 v[220:221], s[78:79], 0, v[134:135]
	s_add_i32 m0, s33, 0x2000
	s_nop 0
	global_load_lds_dwordx4 v[220:221], off
	v_lshl_add_u64 v[220:221], s[44:45], 0, v[128:129]
	s_mov_b32 m0, s39
	s_nop 0
	global_load_lds_dwordx4 v[220:221], off
	s_mov_b32 m0, s55
	s_nop 0
	global_load_lds_dwordx4 v[222:223], off
	s_cmp_eq_u32 s77, 1
	s_cbranch_scc1 .Lds7_1_a
	s_cmp_eq_u32 s77, 5
	s_cbranch_scc1 .Lds7_1_b
; #define PG8_STAGE(bufoff, gbase, voff) do { _Pragma("unroll") for (int _i = 0; _i < 2; ++_i) \
;         __builtin_amdgcn_global_load_lds((const unsigned*)((const char*)(gbase) + (voff)[_i]), (PG8_LAS unsigned*)(lds + (bufoff) + ldsw + _i * 8192), 16, 0, 0); } while (0)
; #define PG8_LDA(dst, b, h) do { _Pragma("unroll") for (int m = 0; m < 4; ++m) _Pragma("unroll") for (int k = 0; k < 2; ++k) dst[m][k] = *(const PG8_LAS bf16x8*)(lds + PG8_SA(b, h) + aoff + m * 2048 + k * 1024); } while (0)
; #define PG8_LDB(dst, b, h) do { _Pragma("unroll") for (int n = 0; n < 2; ++n) _Pragma("unroll") for (int k = 0; k < 2; ++k) dst[n][k] = *(const PG8_LAS bf16x8*)(lds + PG8_SB(b, h) + boff + n * 2048 + k * 1024); } while (0)
; #define PG8_MMA(ai, bj, At, Bt) do { __builtin_amdgcn_s_setprio(1); _Pragma("unroll") for (int m = 0; m < 4; ++m) _Pragma("unroll") for (int n = 0; n < 2; ++n) _Pragma("unroll") for (int k = 0; k < 2; ++k) \
;         acc[ai][bj][m][n] = __builtin_amdgcn_mfma_f32_16x16x32_bf16(Bt[n][k], At[m][k], acc[ai][bj][m][n], 0, 0, 0); __builtin_amdgcn_s_setprio(0); } while (0)
; #define PG8_WAIT_V(n) asm volatile("s_waitcnt vmcnt(" #n ")" ::: "memory")
; #define PG8_WAIT_L(n) asm volatile("s_waitcnt lgkmcnt(" #n ")" ::: "memory")
; #define PG8_BAR __builtin_amdgcn_s_barrier()
; #define PG8_SCHED __builtin_amdgcn_sched_barrier(0)
; template <class Epi, class Sched, bool ALIGN_EPI = false, bool SP2 = false>
; __device__ __forceinline__ void gemm_phase(PG8_LAS unsigned char* lds, const Gemm g, const Sched& S, const Epi& E) {
;     ...
;             PG8_LDA(At, 0, 1); PG8_STAGE(PG8_SB(0, 0), b2, voffB); PG8_STAGE(PG8_SB(0, 1), b2 + hstep, voffB); PG8_STAGE(PG8_SA(0, 0), a2, voffA);
;             PG8_WAIT_V(8); PG8_WAIT_L(0); PG8_BAR; PG8_MMA(1, 0, At, B0); PG8_MMA(1, 1, At, B1); PG8_BAR; PG8_SCHED;
;             PG8_LDB(B0, 1, 0); PG8_LDB(B1, 1, 1); PG8_SCHED; PG8_LDA(At, 1, 0); PG8_STAGE(PG8_SA(0, 1), a2 + hstep, voffA);
.Lds7_1_ret:
	s_waitcnt vmcnt(8)
	s_waitcnt lgkmcnt(0)
	s_barrier
	s_setprio 1
	s_waitcnt lgkmcnt(0)
	v_mfma_f32_16x16x32_bf16 v[60:63], v[154:157], v[186:189], v[60:63]
	v_mfma_f32_16x16x32_bf16 v[52:55], v[162:165], v[186:189], v[52:55]
	v_mfma_f32_16x16x32_bf16 v[44:47], v[154:157], v[194:197], v[44:47]
	v_mfma_f32_16x16x32_bf16 v[36:39], v[162:165], v[194:197], v[36:39]
	v_mfma_f32_16x16x32_bf16 v[28:31], v[154:157], v[202:205], v[28:31]
	v_mfma_f32_16x16x32_bf16 v[20:23], v[162:165], v[202:205], v[20:23]
	v_mfma_f32_16x16x32_bf16 v[12:15], v[154:157], v[210:213], v[12:15]
	v_mfma_f32_16x16x32_bf16 v[4:7], v[162:165], v[210:213], v[4:7]
	v_mfma_f32_16x16x32_bf16 v[60:63], v[158:161], v[190:193], v[60:63]
	v_mfma_f32_16x16x32_bf16 v[52:55], v[166:169], v[190:193], v[52:55]
	v_mfma_f32_16x16x32_bf16 v[44:47], v[158:161], v[198:201], v[44:47]
	v_mfma_f32_16x16x32_bf16 v[36:39], v[166:169], v[198:201], v[36:39]
	v_mfma_f32_16x16x32_bf16 v[28:31], v[158:161], v[206:209], v[28:31]
	v_mfma_f32_16x16x32_bf16 v[20:23], v[166:169], v[206:209], v[20:23]
	v_mfma_f32_16x16x32_bf16 v[12:15], v[158:161], v[214:217], v[12:15]
	v_mfma_f32_16x16x32_bf16 v[4:7], v[166:169], v[214:217], v[4:7]
	s_setprio 0
	s_setprio 1
	v_mfma_f32_16x16x32_bf16 v[56:59], v[170:173], v[186:189], v[56:59]
	v_mfma_f32_16x16x32_bf16 v[48:51], v[178:181], v[186:189], v[48:51]
	v_mfma_f32_16x16x32_bf16 v[40:43], v[170:173], v[194:197], v[40:43]
	v_mfma_f32_16x16x32_bf16 v[32:35], v[178:181], v[194:197], v[32:35]
	v_mfma_f32_16x16x32_bf16 v[24:27], v[170:173], v[202:205], v[24:27]
	v_mfma_f32_16x16x32_bf16 v[16:19], v[178:181], v[202:205], v[16:19]
	v_mfma_f32_16x16x32_bf16 v[8:11], v[170:173], v[210:213], v[8:11]
	v_mfma_f32_16x16x32_bf16 v[0:3], v[178:181], v[210:213], v[0:3]
	v_mfma_f32_16x16x32_bf16 v[56:59], v[174:177], v[190:193], v[56:59]
	v_mfma_f32_16x16x32_bf16 v[48:51], v[182:185], v[190:193], v[48:51]
	v_mfma_f32_16x16x32_bf16 v[40:43], v[174:177], v[198:201], v[40:43]
	v_mfma_f32_16x16x32_bf16 v[32:35], v[182:185], v[198:201], v[32:35]
	v_mfma_f32_16x16x32_bf16 v[24:27], v[174:177], v[206:209], v[24:27]
	v_mfma_f32_16x16x32_bf16 v[16:19], v[182:185], v[206:209], v[16:19]
	v_mfma_f32_16x16x32_bf16 v[8:11], v[174:177], v[214:217], v[8:11]
	v_mfma_f32_16x16x32_bf16 v[0:3], v[182:185], v[214:217], v[0:3]
	s_setprio 0
	s_barrier
	s_add_i32 s33, 0, 0x18000
	v_add_u32_e32 v153, s33, v145
	s_add_i32 s34, 0, 0x1c000
	ds_read_b128 v[154:157], v153
	ds_read_b128 v[158:161], v153 offset:1024
	ds_read_b128 v[162:165], v153 offset:2048
	ds_read_b128 v[166:169], v153 offset:3072
	v_add_u32_e32 v153, s34, v145
	ds_read_b128 v[170:173], v153
	ds_read_b128 v[174:177], v153 offset:1024
	ds_read_b128 v[178:181], v153 offset:2048
	ds_read_b128 v[182:185], v153 offset:3072
	s_add_u32 s44, s44, 0x40000
	s_addc_u32 s45, s45, 0
	s_mov_b32 m0, s56
	v_lshl_add_u64 v[224:225], s[44:45], 0, v[128:129]
	ds_read_b128 v[186:189], v149 offset:32768
	ds_read_b128 v[190:193], v149 offset:33792
	ds_read_b128 v[194:197], v149 offset:34816
	ds_read_b128 v[198:201], v149 offset:35840
	ds_read_b128 v[202:205], v149 offset:36864
	ds_read_b128 v[206:209], v149 offset:37888
	ds_read_b128 v[210:213], v149 offset:38912
	ds_read_b128 v[214:217], v149 offset:39936
	global_load_lds_dwordx4 v[224:225], off
	v_lshl_add_u64 v[224:225], s[44:45], 0, v[132:133]
	s_mov_b32 m0, s57
	s_nop 0
	global_load_lds_dwordx4 v[224:225], off
	s_cmp_eq_u32 s77, 2
	s_cbranch_scc1 .Lds7_2_a
.Lds7_2_ret:
	s_waitcnt vmcnt(8)
	s_waitcnt lgkmcnt(0)
	s_barrier
	s_setprio 1
	s_waitcnt lgkmcnt(0)
	v_mfma_f32_16x16x32_bf16 v[124:127], v[154:157], v[186:189], v[124:127]
	v_mfma_f32_16x16x32_bf16 v[116:119], v[162:165], v[186:189], v[116:119]
	v_mfma_f32_16x16x32_bf16 v[108:111], v[154:157], v[194:197], v[108:111]
	v_mfma_f32_16x16x32_bf16 v[100:103], v[162:165], v[194:197], v[100:103]
	v_mfma_f32_16x16x32_bf16 v[92:95], v[154:157], v[202:205], v[92:95]
	v_mfma_f32_16x16x32_bf16 v[84:87], v[162:165], v[202:205], v[84:87]
	v_mfma_f32_16x16x32_bf16 v[76:79], v[154:157], v[210:213], v[76:79]
	v_mfma_f32_16x16x32_bf16 v[68:71], v[162:165], v[210:213], v[68:71]
	v_mfma_f32_16x16x32_bf16 v[124:127], v[158:161], v[190:193], v[124:127]
	v_mfma_f32_16x16x32_bf16 v[116:119], v[166:169], v[190:193], v[116:119]
	v_mfma_f32_16x16x32_bf16 v[108:111], v[158:161], v[198:201], v[108:111]
	v_mfma_f32_16x16x32_bf16 v[100:103], v[166:169], v[198:201], v[100:103]
	v_mfma_f32_16x16x32_bf16 v[92:95], v[158:161], v[206:209], v[92:95]
	v_mfma_f32_16x16x32_bf16 v[84:87], v[166:169], v[206:209], v[84:87]
	v_mfma_f32_16x16x32_bf16 v[76:79], v[158:161], v[214:217], v[76:79]
	v_mfma_f32_16x16x32_bf16 v[68:71], v[166:169], v[214:217], v[68:71]
	s_setprio 0
	s_setprio 1
	v_mfma_f32_16x16x32_bf16 v[120:123], v[170:173], v[186:189], v[120:123]
	v_mfma_f32_16x16x32_bf16 v[112:115], v[178:181], v[186:189], v[112:115]
	v_mfma_f32_16x16x32_bf16 v[104:107], v[170:173], v[194:197], v[104:107]
	v_mfma_f32_16x16x32_bf16 v[96:99], v[178:181], v[194:197], v[96:99]
	v_mfma_f32_16x16x32_bf16 v[88:91], v[170:173], v[202:205], v[88:91]
	v_mfma_f32_16x16x32_bf16 v[80:83], v[178:181], v[202:205], v[80:83]
	v_mfma_f32_16x16x32_bf16 v[72:75], v[170:173], v[210:213], v[72:75]
	v_mfma_f32_16x16x32_bf16 v[64:67], v[178:181], v[210:213], v[64:67]
	v_mfma_f32_16x16x32_bf16 v[120:123], v[174:177], v[190:193], v[120:123]
	v_mfma_f32_16x16x32_bf16 v[112:115], v[182:185], v[190:193], v[112:115]
	v_mfma_f32_16x16x32_bf16 v[104:107], v[174:177], v[198:201], v[104:107]
	v_mfma_f32_16x16x32_bf16 v[96:99], v[182:185], v[198:201], v[96:99]
	v_mfma_f32_16x16x32_bf16 v[88:91], v[174:177], v[206:209], v[88:91]
	v_mfma_f32_16x16x32_bf16 v[80:83], v[182:185], v[206:209], v[80:83]
	v_mfma_f32_16x16x32_bf16 v[72:75], v[174:177], v[214:217], v[72:75]
	v_mfma_f32_16x16x32_bf16 v[64:67], v[182:185], v[214:217], v[64:67]
	s_setprio 0
	s_barrier
; __device__ __forceinline__ unsigned pk2(float lo, float hi) { f32x2 v = {lo, hi}; bf16x2_t b = __builtin_convertvector(v, bf16x2_t); return __builtin_bit_cast(unsigned, b); }
; __device__ __forceinline__ float silu_f(float a) { return a * __builtin_amdgcn_rcpf(1.0f + __expf(-a)); }
; #define PG8_STAGE(bufoff, gbase, voff) do { _Pragma("unroll") for (int _i = 0; _i < 2; ++_i) \
;         __builtin_amdgcn_global_load_lds((const unsigned*)((const char*)(gbase) + (voff)[_i]), (PG8_LAS unsigned*)(lds + (bufoff) + ldsw + _i * 8192), 16, 0, 0); } while (0)
; #define PG8_LDA(dst, b, h) do { _Pragma("unroll") for (int m = 0; m < 4; ++m) _Pragma("unroll") for (int k = 0; k < 2; ++k) dst[m][k] = *(const PG8_LAS bf16x8*)(lds + PG8_SA(b, h) + aoff + m * 2048 + k * 1024); } while (0)
; #define PG8_BAR __builtin_amdgcn_s_barrier()
;     __device__ __forceinline__ void operator()(const f32x4 (&acc)[2][2][4][2], const Unit& u, int wr, int wc, int fr, int fq) const {
;         const int row0 = u.pm * BM + wr * 64 + fr; const int col0 = u.pn * HALF + wc * 32 + 8 * fq;
; #pragma unroll
;         for (int ai = 0; ai < 2; ++ai)
; #pragma unroll
;             for (int m = 0; m < 4; ++m) { const int row = row0 + ai * HALF + m * 16;
;                 const f32x4 a0 = acc[ai][0][m][0], a1 = acc[ai][0][m][1], b0 = acc[ai][1][m][0], b1 = acc[ai][1][m][1];
;                 u32x4 w; w.x = pk2(silu_f(a0[0]) * b0[0], silu_f(a0[1]) * b0[1]); w.y = pk2(silu_f(a0[2]) * b0[2], silu_f(a0[3]) * b0[3]);
;                 w.z = pk2(silu_f(a1[0]) * b1[0], silu_f(a1[1]) * b1[1]); w.w = pk2(silu_f(a1[2]) * b1[2], silu_f(a1[3]) * b1[3]);
;                 *(u32x4*)(H + (size_t)row * ldh + col0) = w; }
; template <class Epi, class Sched, bool ALIGN_EPI = false, bool SP2 = false>
; __device__ __forceinline__ void gemm_phase(PG8_LAS unsigned char* lds, const Gemm g, const Sched& S, const Epi& E) {
;     ...
;             PG8_LDB(B0, 1, 0); PG8_LDB(B1, 1, 1); PG8_SCHED; PG8_LDA(At, 1, 0); PG8_STAGE(PG8_SA(0, 1), a2 + hstep, voffA);
;             PG8_WAIT_V(8); PG8_WAIT_L(0); PG8_BAR; PG8_MMA(0, 0, At, B0); PG8_MMA(0, 1, At, B1); PG8_BAR; PG8_SCHED;
;             PG8_LDA(At, 1, 1); PG8_STAGE(PG8_SB(1, 0), b3, voffB); PG8_STAGE(PG8_SB(1, 1), b3 + hstep, voffB); PG8_STAGE(PG8_SA(1, 0), a3, voffA);
;             PG8_WAIT_V(8); PG8_WAIT_L(0); PG8_BAR; PG8_MMA(1, 0, At, B0); PG8_MMA(1, 1, At, B1); PG8_BAR; PG8_SCHED;
	s_add_i32 s33, s33, s52
	v_lshl_add_u64 v[150:151], v[150:151], 0, s[10:11]
	s_mov_b32 m0, s33
	ds_read_b128 v[186:189], v149 offset:49152
	ds_read_b128 v[190:193], v149 offset:50176
	ds_read_b128 v[194:197], v149 offset:51200
	ds_read_b128 v[198:201], v149 offset:52224
	ds_read_b128 v[202:205], v149 offset:53248
	ds_read_b128 v[206:209], v149 offset:54272
	ds_read_b128 v[210:213], v149 offset:55296
	ds_read_b128 v[214:217], v149 offset:56320
	global_load_lds_dwordx4 v[150:151], off
	s_add_i32 m0, s33, 0x2000
	s_add_u32 s42, s42, 0x40080
	v_lshl_add_u64 v[150:151], v[218:219], 0, s[10:11]
	s_addc_u32 s43, s43, 0
	s_add_i32 s33, s34, s52
	global_load_lds_dwordx4 v[150:151], off
	v_lshl_add_u64 v[150:151], s[42:43], 0, v[130:131]
	s_mov_b32 m0, s33
	s_nop 0
	global_load_lds_dwordx4 v[150:151], off
	v_lshl_add_u64 v[150:151], s[42:43], 0, v[134:135]
	s_add_i32 m0, s33, 0x2000
	s_nop 0
	global_load_lds_dwordx4 v[150:151], off
	v_lshl_add_u64 v[150:151], v[220:221], 0, s[10:11]
	s_mov_b32 m0, s60
	s_nop 0
	global_load_lds_dwordx4 v[150:151], off
	v_lshl_add_u64 v[150:151], v[222:223], 0, s[10:11]
	s_mov_b32 m0, s61
	s_nop 0
	global_load_lds_dwordx4 v[150:151], off
	s_cmp_eq_u32 s77, 3
	s_cbranch_scc1 .Lds7_3_a
.Lds7_3_ret:
	s_waitcnt vmcnt(8)
	s_waitcnt lgkmcnt(0)
	s_barrier
	s_setprio 1
	s_waitcnt lgkmcnt(0)
	v_mfma_f32_16x16x32_bf16 v[60:63], v[154:157], v[186:189], v[60:63]
	v_mfma_f32_16x16x32_bf16 v[52:55], v[162:165], v[186:189], v[52:55]
	v_mfma_f32_16x16x32_bf16 v[44:47], v[154:157], v[194:197], v[44:47]
	v_mfma_f32_16x16x32_bf16 v[36:39], v[162:165], v[194:197], v[36:39]
	v_mfma_f32_16x16x32_bf16 v[28:31], v[154:157], v[202:205], v[28:31]
	v_mfma_f32_16x16x32_bf16 v[20:23], v[162:165], v[202:205], v[20:23]
	v_mfma_f32_16x16x32_bf16 v[12:15], v[154:157], v[210:213], v[12:15]
	v_mfma_f32_16x16x32_bf16 v[4:7], v[162:165], v[210:213], v[4:7]
	v_mfma_f32_16x16x32_bf16 v[60:63], v[158:161], v[190:193], v[60:63]
	v_mfma_f32_16x16x32_bf16 v[52:55], v[166:169], v[190:193], v[52:55]
	v_mfma_f32_16x16x32_bf16 v[44:47], v[158:161], v[198:201], v[44:47]
	v_mfma_f32_16x16x32_bf16 v[36:39], v[166:169], v[198:201], v[36:39]
	v_mfma_f32_16x16x32_bf16 v[28:31], v[158:161], v[206:209], v[28:31]
	v_mfma_f32_16x16x32_bf16 v[20:23], v[166:169], v[206:209], v[20:23]
	v_mfma_f32_16x16x32_bf16 v[12:15], v[158:161], v[214:217], v[12:15]
	v_mfma_f32_16x16x32_bf16 v[4:7], v[166:169], v[214:217], v[4:7]
	s_setprio 0
	s_setprio 1
	v_mfma_f32_16x16x32_bf16 v[56:59], v[170:173], v[186:189], v[56:59]
	v_mfma_f32_16x16x32_bf16 v[48:51], v[178:181], v[186:189], v[48:51]
	v_mfma_f32_16x16x32_bf16 v[40:43], v[170:173], v[194:197], v[40:43]
	v_mfma_f32_16x16x32_bf16 v[32:35], v[178:181], v[194:197], v[32:35]
	v_mfma_f32_16x16x32_bf16 v[24:27], v[170:173], v[202:205], v[24:27]
	v_mfma_f32_16x16x32_bf16 v[16:19], v[178:181], v[202:205], v[16:19]
	v_mfma_f32_16x16x32_bf16 v[8:11], v[170:173], v[210:213], v[8:11]
	v_mfma_f32_16x16x32_bf16 v[0:3], v[178:181], v[210:213], v[0:3]
	v_mfma_f32_16x16x32_bf16 v[56:59], v[174:177], v[190:193], v[56:59]
	v_mfma_f32_16x16x32_bf16 v[48:51], v[182:185], v[190:193], v[48:51]
	v_mfma_f32_16x16x32_bf16 v[40:43], v[174:177], v[198:201], v[40:43]
	v_mfma_f32_16x16x32_bf16 v[32:35], v[182:185], v[198:201], v[32:35]
	v_mfma_f32_16x16x32_bf16 v[24:27], v[174:177], v[206:209], v[24:27]
	v_mfma_f32_16x16x32_bf16 v[16:19], v[182:185], v[206:209], v[16:19]
	v_mfma_f32_16x16x32_bf16 v[8:11], v[174:177], v[214:217], v[8:11]
	v_mfma_f32_16x16x32_bf16 v[0:3], v[182:185], v[214:217], v[0:3]
	s_setprio 0
	s_barrier
	s_add_i32 s76, s76, 2
	s_add_u32 s40, s40, 0x100
	s_addc_u32 s41, s41, 0
	s_add_u32 s74, s74, 0x100
	s_addc_u32 s75, s75, 0
	s_cmp_gt_u32 s76, 13
	s_cbranch_scc0 .LBB0_714
	s_and_b64 vcc, exec, s[12:13]
	s_cbranch_vccz .LBB0_717
	s_barrier
.LBB0_717:
	v_mul_f32_e32 v151, 0xbfb8aa3b, v124
	v_exp_f32_e32 v151, v151
	v_mul_f32_e32 v153, 0xbfb8aa3b, v125
	v_exp_f32_e32 v153, v153
	v_mul_f32_e32 v157, 0xbfb8aa3b, v127
	v_add_f32_e32 v151, 1.0, v151
	v_rcp_f32_e32 v156, v151
	v_add_f32_e32 v151, 1.0, v153
	v_mul_f32_e32 v153, 0xbfb8aa3b, v126
	v_exp_f32_e32 v153, v153
	v_exp_f32_e32 v159, v157
	v_rcp_f32_e32 v157, v151
	v_lshl_or_b32 v154, s71, 7, v146
	v_add_f32_e32 v151, 1.0, v153
	v_rcp_f32_e32 v158, v151
	v_add_f32_e32 v151, 1.0, v159
	v_rcp_f32_e32 v159, v151
	v_pk_mul_f32 v[124:125], v[124:125], v[156:157]
	v_lshl_add_u32 v150, s38, 8, v144
	v_pk_mul_f32 v[120:121], v[124:125], v[120:121]
	v_pk_mul_f32 v[124:125], v[126:127], v[158:159]
	v_cvt_pk_bf16_f32 v120, v120, v121
	v_mul_f32_e32 v121, 0xbfb8aa3b, v116
	v_pk_mul_f32 v[122:123], v[124:125], v[122:123]
	v_exp_f32_e32 v124, v121
	v_mul_f32_e32 v121, 0xbfb8aa3b, v117
	v_exp_f32_e32 v125, v121
	v_cvt_pk_bf16_f32 v121, v122, v123
	v_add_f32_e32 v122, 1.0, v124
	v_mul_f32_e32 v124, 0xbfb8aa3b, v118
	v_add_f32_e32 v123, 1.0, v125
	v_mul_f32_e32 v125, 0xbfb8aa3b, v119
	v_exp_f32_e32 v124, v124
	v_exp_f32_e32 v125, v125
	v_rcp_f32_e32 v122, v122
	v_rcp_f32_e32 v123, v123
	v_add_f32_e32 v124, 1.0, v124
	v_add_f32_e32 v125, 1.0, v125
	v_rcp_f32_e32 v124, v124
	v_rcp_f32_e32 v125, v125
	v_pk_mul_f32 v[116:117], v[116:117], v[122:123]
	v_ashrrev_i32_e32 v155, 31, v154
	v_pk_mul_f32 v[112:113], v[116:117], v[112:113]
	s_andn2_b64 vcc, exec, s[0:1]
	v_cvt_pk_bf16_f32 v122, v112, v113
	v_pk_mul_f32 v[112:113], v[118:119], v[124:125]
	v_mul_f32_e32 v118, 0xbfb8aa3b, v110
	v_pk_mul_f32 v[112:113], v[112:113], v[114:115]
	v_lshlrev_b64 v[114:115], 1, v[154:155]
	v_cvt_pk_bf16_f32 v123, v112, v113
	v_mov_b64_e32 v[112:113], s[8:9]
	v_mad_i64_i32 v[116:117], s[40:41], v150, s70, v[112:113]
; __device__ __forceinline__ unsigned pk2(float lo, float hi) { f32x2 v = {lo, hi}; bf16x2_t b = __builtin_convertvector(v, bf16x2_t); return __builtin_bit_cast(unsigned, b); }
; __device__ __forceinline__ float silu_f(float a) { return a * __builtin_amdgcn_rcpf(1.0f + __expf(-a)); }
;     __device__ __forceinline__ void operator()(const f32x4 (&acc)[2][2][4][2], const Unit& u, int wr, int wc, int fr, int fq) const {
;         const int row0 = u.pm * BM + wr * 64 + fr; const int col0 = u.pn * HALF + wc * 32 + 8 * fq;
; #pragma unroll
;         for (int ai = 0; ai < 2; ++ai)
; #pragma unroll
;             for (int m = 0; m < 4; ++m) { const int row = row0 + ai * HALF + m * 16;
;                 const f32x4 a0 = acc[ai][0][m][0], a1 = acc[ai][0][m][1], b0 = acc[ai][1][m][0], b1 = acc[ai][1][m][1];
;                 u32x4 w; w.x = pk2(silu_f(a0[0]) * b0[0], silu_f(a0[1]) * b0[1]); w.y = pk2(silu_f(a0[2]) * b0[2], silu_f(a0[3]) * b0[3]);
;                 w.z = pk2(silu_f(a1[0]) * b1[0], silu_f(a1[1]) * b1[1]); w.w = pk2(silu_f(a1[2]) * b1[2], silu_f(a1[3]) * b1[3]);
;                 *(u32x4*)(H + (size_t)row * ldh + col0) = w; }
	v_lshl_add_u64 v[116:117], v[116:117], 0, v[114:115]
	global_store_dwordx4 v[116:117], v[120:123], off
	v_mad_u32_u24 v229, v150, s70, v114
	v_mul_f32_e32 v116, 0xbfb8aa3b, v108
	v_mul_f32_e32 v117, 0xbfb8aa3b, v109
	v_exp_f32_e32 v116, v116
	v_exp_f32_e32 v117, v117
	v_mul_f32_e32 v119, 0xbfb8aa3b, v111
	v_exp_f32_e32 v118, v118
	v_exp_f32_e32 v119, v119
	v_add_f32_e32 v116, 1.0, v116
	v_add_f32_e32 v117, 1.0, v117
	v_rcp_f32_e32 v116, v116
	v_rcp_f32_e32 v117, v117
	v_add_f32_e32 v118, 1.0, v118
	v_add_f32_e32 v119, 1.0, v119
	v_rcp_f32_e32 v118, v118
	v_rcp_f32_e32 v119, v119
	v_pk_mul_f32 v[108:109], v[108:109], v[116:117]
	v_or_b32_e32 v120, 16, v150
	v_pk_mul_f32 v[104:105], v[108:109], v[104:105]
	v_pk_mul_f32 v[108:109], v[110:111], v[118:119]
	v_cvt_pk_bf16_f32 v104, v104, v105
	v_mul_f32_e32 v105, 0xbfb8aa3b, v100
	v_pk_mul_f32 v[106:107], v[108:109], v[106:107]
	v_exp_f32_e32 v108, v105
	v_mul_f32_e32 v105, 0xbfb8aa3b, v101
	v_exp_f32_e32 v109, v105
	v_cvt_pk_bf16_f32 v105, v106, v107
	v_add_f32_e32 v106, 1.0, v108
	v_mul_f32_e32 v108, 0xbfb8aa3b, v102
	v_add_f32_e32 v107, 1.0, v109
	v_mul_f32_e32 v109, 0xbfb8aa3b, v103
	v_exp_f32_e32 v108, v108
	v_exp_f32_e32 v109, v109
	v_rcp_f32_e32 v106, v106
	v_rcp_f32_e32 v107, v107
	v_add_f32_e32 v108, 1.0, v108
	v_add_f32_e32 v109, 1.0, v109
	v_rcp_f32_e32 v108, v108
	v_rcp_f32_e32 v109, v109
	v_pk_mul_f32 v[100:101], v[100:101], v[106:107]
	s_mov_b64 s[0:1], -1
	v_pk_mul_f32 v[96:97], v[100:101], v[96:97]
	v_or_b32_e32 v100, 32, v150
	v_cvt_pk_bf16_f32 v106, v96, v97
	v_pk_mul_f32 v[96:97], v[102:103], v[108:109]
	s_nop 0
	v_pk_mul_f32 v[96:97], v[96:97], v[98:99]
	v_mul_f32_e32 v98, 0xbfb8aa3b, v94
	v_cvt_pk_bf16_f32 v107, v96, v97
	v_mad_i64_i32 v[96:97], s[40:41], v120, s70, v[112:113]
	v_lshl_add_u64 v[96:97], v[96:97], 0, v[114:115]
	global_store_dwordx4 v[96:97], v[104:107], off
	v_mul_f32_e32 v96, 0xbfb8aa3b, v92
	v_mul_f32_e32 v97, 0xbfb8aa3b, v93
	v_exp_f32_e32 v96, v96
	v_exp_f32_e32 v97, v97
	v_mul_f32_e32 v99, 0xbfb8aa3b, v95
	v_exp_f32_e32 v98, v98
	v_exp_f32_e32 v99, v99
	v_add_f32_e32 v96, 1.0, v96
	v_add_f32_e32 v97, 1.0, v97
	v_rcp_f32_e32 v96, v96
	v_rcp_f32_e32 v97, v97
	v_add_f32_e32 v98, 1.0, v98
	v_add_f32_e32 v99, 1.0, v99
	v_rcp_f32_e32 v98, v98
	v_rcp_f32_e32 v99, v99
	v_pk_mul_f32 v[92:93], v[92:93], v[96:97]
	s_nop 0
	v_pk_mul_f32 v[88:89], v[92:93], v[88:89]
	v_pk_mul_f32 v[92:93], v[94:95], v[98:99]
	v_cvt_pk_bf16_f32 v230, v88, v89
	v_mul_f32_e32 v89, 0xbfb8aa3b, v84
	v_pk_mul_f32 v[90:91], v[92:93], v[90:91]
	v_exp_f32_e32 v92, v89
	v_mul_f32_e32 v89, 0xbfb8aa3b, v85
	v_exp_f32_e32 v93, v89
	v_cvt_pk_bf16_f32 v231, v90, v91
	v_add_f32_e32 v90, 1.0, v92
	v_mul_f32_e32 v92, 0xbfb8aa3b, v86
	v_add_f32_e32 v91, 1.0, v93
	v_mul_f32_e32 v93, 0xbfb8aa3b, v87
	v_exp_f32_e32 v92, v92
	v_exp_f32_e32 v93, v93
	v_rcp_f32_e32 v90, v90
	v_rcp_f32_e32 v91, v91
	v_add_f32_e32 v92, 1.0, v92
	v_add_f32_e32 v93, 1.0, v93
	v_rcp_f32_e32 v92, v92
	v_rcp_f32_e32 v93, v93
	v_pk_mul_f32 v[84:85], v[84:85], v[90:91]
	s_nop 0
	v_pk_mul_f32 v[80:81], v[84:85], v[80:81]
	v_or_b32_e32 v84, 48, v150
	v_cvt_pk_bf16_f32 v232, v80, v81
	v_pk_mul_f32 v[80:81], v[86:87], v[92:93]
	s_nop 0
	v_pk_mul_f32 v[80:81], v[80:81], v[82:83]
	v_mul_f32_e32 v82, 0xbfb8aa3b, v78
	v_cvt_pk_bf16_f32 v233, v80, v81
	s_nop 0
	v_mul_f32_e32 v80, 0xbfb8aa3b, v76
	v_mul_f32_e32 v81, 0xbfb8aa3b, v77
	v_exp_f32_e32 v80, v80
	v_exp_f32_e32 v81, v81
	v_mul_f32_e32 v83, 0xbfb8aa3b, v79
	v_exp_f32_e32 v82, v82
	v_exp_f32_e32 v83, v83
	v_add_f32_e32 v80, 1.0, v80
	v_add_f32_e32 v81, 1.0, v81
	v_rcp_f32_e32 v80, v80
	v_rcp_f32_e32 v81, v81
	v_add_f32_e32 v82, 1.0, v82
	v_add_f32_e32 v83, 1.0, v83
	v_rcp_f32_e32 v82, v82
	v_rcp_f32_e32 v83, v83
	v_pk_mul_f32 v[76:77], v[76:77], v[80:81]
	s_nop 0
	v_pk_mul_f32 v[72:73], v[76:77], v[72:73]
	v_pk_mul_f32 v[76:77], v[78:79], v[82:83]
	v_cvt_pk_bf16_f32 v234, v72, v73
	v_mul_f32_e32 v73, 0xbfb8aa3b, v68
	v_pk_mul_f32 v[74:75], v[76:77], v[74:75]
	v_exp_f32_e32 v76, v73
	v_mul_f32_e32 v73, 0xbfb8aa3b, v69
	v_exp_f32_e32 v77, v73
	v_cvt_pk_bf16_f32 v235, v74, v75
	v_add_f32_e32 v74, 1.0, v76
	v_mul_f32_e32 v76, 0xbfb8aa3b, v70
	v_add_f32_e32 v75, 1.0, v77
	v_mul_f32_e32 v77, 0xbfb8aa3b, v71
	v_exp_f32_e32 v76, v76
	v_exp_f32_e32 v77, v77
	v_rcp_f32_e32 v74, v74
	v_rcp_f32_e32 v75, v75
	v_add_f32_e32 v76, 1.0, v76
	v_add_f32_e32 v77, 1.0, v77
	v_rcp_f32_e32 v76, v76
	v_rcp_f32_e32 v77, v77
	v_pk_mul_f32 v[68:69], v[68:69], v[74:75]
	s_nop 0
	v_pk_mul_f32 v[64:65], v[68:69], v[64:65]
	v_add_u32_e32 v68, 0x80, v150
	v_cvt_pk_bf16_f32 v236, v64, v65
	v_pk_mul_f32 v[64:65], v[70:71], v[76:77]
	s_nop 0
	v_pk_mul_f32 v[64:65], v[64:65], v[66:67]
	v_mul_f32_e32 v66, 0xbfb8aa3b, v62
	v_cvt_pk_bf16_f32 v237, v64, v65
	s_nop 0
	v_mul_f32_e32 v64, 0xbfb8aa3b, v60
	v_mul_f32_e32 v65, 0xbfb8aa3b, v61
	v_exp_f32_e32 v64, v64
	v_exp_f32_e32 v65, v65
	v_mul_f32_e32 v67, 0xbfb8aa3b, v63
	v_exp_f32_e32 v66, v66
	v_exp_f32_e32 v67, v67
	v_add_f32_e32 v64, 1.0, v64
	v_add_f32_e32 v65, 1.0, v65
	v_rcp_f32_e32 v64, v64
	v_rcp_f32_e32 v65, v65
	v_add_f32_e32 v66, 1.0, v66
	v_add_f32_e32 v67, 1.0, v67
	v_rcp_f32_e32 v66, v66
	v_rcp_f32_e32 v67, v67
	v_pk_mul_f32 v[60:61], v[60:61], v[64:65]
	s_nop 0
	v_pk_mul_f32 v[56:57], v[60:61], v[56:57]
	v_pk_mul_f32 v[60:61], v[62:63], v[66:67]
	v_cvt_pk_bf16_f32 v238, v56, v57
	v_mul_f32_e32 v57, 0xbfb8aa3b, v52
	v_pk_mul_f32 v[58:59], v[60:61], v[58:59]
	v_exp_f32_e32 v60, v57
	v_mul_f32_e32 v57, 0xbfb8aa3b, v53
	v_exp_f32_e32 v61, v57
	v_cvt_pk_bf16_f32 v239, v58, v59
	v_add_f32_e32 v58, 1.0, v60
	v_mul_f32_e32 v60, 0xbfb8aa3b, v54
	v_add_f32_e32 v59, 1.0, v61
; __device__ __forceinline__ unsigned pk2(float lo, float hi) { f32x2 v = {lo, hi}; bf16x2_t b = __builtin_convertvector(v, bf16x2_t); return __builtin_bit_cast(unsigned, b); }
; __device__ __forceinline__ float silu_f(float a) { return a * __builtin_amdgcn_rcpf(1.0f + __expf(-a)); }
; #define PG8_WAIT_V(n) asm volatile("s_waitcnt vmcnt(" #n ")" ::: "memory")
; #define PG8_BAR __builtin_amdgcn_s_barrier()
;     __device__ __forceinline__ void operator()(const f32x4 (&acc)[2][2][4][2], const Unit& u, int wr, int wc, int fr, int fq) const {
;         const int row0 = u.pm * BM + wr * 64 + fr; const int col0 = u.pn * HALF + wc * 32 + 8 * fq;
; #pragma unroll
;         for (int ai = 0; ai < 2; ++ai)
; #pragma unroll
;             for (int m = 0; m < 4; ++m) { const int row = row0 + ai * HALF + m * 16;
;                 const f32x4 a0 = acc[ai][0][m][0], a1 = acc[ai][0][m][1], b0 = acc[ai][1][m][0], b1 = acc[ai][1][m][1];
;                 u32x4 w; w.x = pk2(silu_f(a0[0]) * b0[0], silu_f(a0[1]) * b0[1]); w.y = pk2(silu_f(a0[2]) * b0[2], silu_f(a0[3]) * b0[3]);
;                 w.z = pk2(silu_f(a1[0]) * b1[0], silu_f(a1[1]) * b1[1]); w.w = pk2(silu_f(a1[2]) * b1[2], silu_f(a1[3]) * b1[3]);
;                 *(u32x4*)(H + (size_t)row * ldh + col0) = w; }
; template <class Epi, class Sched, bool ALIGN_EPI = false, bool SP2 = false>
; __device__ __forceinline__ void gemm_phase(PG8_LAS unsigned char* lds, const Gemm g, const Sched& S, const Epi& E) {
;     ...
;     PG8_WAIT_V(0);
;     if constexpr (!ALIGN_EPI) { if (wr == 0) PG8_BAR; }
;     PG8_BAR;
	v_mul_f32_e32 v61, 0xbfb8aa3b, v55
	v_exp_f32_e32 v60, v60
	v_exp_f32_e32 v61, v61
	v_rcp_f32_e32 v58, v58
	v_rcp_f32_e32 v59, v59
	v_add_f32_e32 v60, 1.0, v60
	v_add_f32_e32 v61, 1.0, v61
	v_rcp_f32_e32 v60, v60
	v_rcp_f32_e32 v61, v61
	v_pk_mul_f32 v[52:53], v[52:53], v[58:59]
	s_nop 0
	v_pk_mul_f32 v[48:49], v[52:53], v[48:49]
	v_add_u32_e32 v52, 0x90, v150
	v_cvt_pk_bf16_f32 v240, v48, v49
	v_pk_mul_f32 v[48:49], v[54:55], v[60:61]
	s_nop 0
	v_pk_mul_f32 v[48:49], v[48:49], v[50:51]
	v_mul_f32_e32 v50, 0xbfb8aa3b, v46
	v_cvt_pk_bf16_f32 v241, v48, v49
	s_nop 0
	v_mul_f32_e32 v48, 0xbfb8aa3b, v44
	v_mul_f32_e32 v49, 0xbfb8aa3b, v45
	v_exp_f32_e32 v48, v48
	v_exp_f32_e32 v49, v49
	v_mul_f32_e32 v51, 0xbfb8aa3b, v47
	v_exp_f32_e32 v50, v50
	v_exp_f32_e32 v51, v51
	v_add_f32_e32 v48, 1.0, v48
	v_add_f32_e32 v49, 1.0, v49
	v_rcp_f32_e32 v48, v48
	v_rcp_f32_e32 v49, v49
	v_add_f32_e32 v50, 1.0, v50
	v_add_f32_e32 v51, 1.0, v51
	v_rcp_f32_e32 v50, v50
	v_rcp_f32_e32 v51, v51
	v_pk_mul_f32 v[44:45], v[44:45], v[48:49]
	s_nop 0
	v_pk_mul_f32 v[40:41], v[44:45], v[40:41]
	v_pk_mul_f32 v[44:45], v[46:47], v[50:51]
	v_cvt_pk_bf16_f32 v242, v40, v41
	v_mul_f32_e32 v41, 0xbfb8aa3b, v36
	v_pk_mul_f32 v[42:43], v[44:45], v[42:43]
	v_exp_f32_e32 v44, v41
	v_mul_f32_e32 v41, 0xbfb8aa3b, v37
	v_exp_f32_e32 v45, v41
	v_cvt_pk_bf16_f32 v243, v42, v43
	v_add_f32_e32 v42, 1.0, v44
	v_mul_f32_e32 v44, 0xbfb8aa3b, v38
	v_add_f32_e32 v43, 1.0, v45
	v_mul_f32_e32 v45, 0xbfb8aa3b, v39
	v_exp_f32_e32 v44, v44
	v_exp_f32_e32 v45, v45
	v_rcp_f32_e32 v42, v42
	v_rcp_f32_e32 v43, v43
	v_add_f32_e32 v44, 1.0, v44
	v_add_f32_e32 v45, 1.0, v45
	v_rcp_f32_e32 v44, v44
	v_rcp_f32_e32 v45, v45
	v_pk_mul_f32 v[36:37], v[36:37], v[42:43]
	s_nop 0
	v_pk_mul_f32 v[32:33], v[36:37], v[32:33]
	v_add_u32_e32 v36, 0xa0, v150
	v_cvt_pk_bf16_f32 v244, v32, v33
	v_pk_mul_f32 v[32:33], v[38:39], v[44:45]
	s_nop 0
	v_pk_mul_f32 v[32:33], v[32:33], v[34:35]
	v_mul_f32_e32 v34, 0xbfb8aa3b, v30
	v_cvt_pk_bf16_f32 v245, v32, v33
	s_nop 0
	v_mul_f32_e32 v32, 0xbfb8aa3b, v28
	v_mul_f32_e32 v33, 0xbfb8aa3b, v29
	v_exp_f32_e32 v32, v32
	v_exp_f32_e32 v33, v33
	v_mul_f32_e32 v35, 0xbfb8aa3b, v31
	v_exp_f32_e32 v34, v34
	v_exp_f32_e32 v35, v35
	v_add_f32_e32 v32, 1.0, v32
	v_add_f32_e32 v33, 1.0, v33
	v_rcp_f32_e32 v32, v32
	v_rcp_f32_e32 v33, v33
	v_add_f32_e32 v34, 1.0, v34
	v_add_f32_e32 v35, 1.0, v35
	v_rcp_f32_e32 v34, v34
	v_rcp_f32_e32 v35, v35
	v_pk_mul_f32 v[28:29], v[28:29], v[32:33]
	s_nop 0
	v_pk_mul_f32 v[24:25], v[28:29], v[24:25]
	v_pk_mul_f32 v[28:29], v[30:31], v[34:35]
	v_cvt_pk_bf16_f32 v246, v24, v25
	v_mul_f32_e32 v25, 0xbfb8aa3b, v20
	v_pk_mul_f32 v[26:27], v[28:29], v[26:27]
	v_exp_f32_e32 v28, v25
	v_mul_f32_e32 v25, 0xbfb8aa3b, v21
	v_exp_f32_e32 v29, v25
	v_cvt_pk_bf16_f32 v247, v26, v27
	v_add_f32_e32 v26, 1.0, v28
	v_mul_f32_e32 v28, 0xbfb8aa3b, v22
	v_add_f32_e32 v27, 1.0, v29
	v_mul_f32_e32 v29, 0xbfb8aa3b, v23
	v_exp_f32_e32 v28, v28
	v_exp_f32_e32 v29, v29
	v_rcp_f32_e32 v26, v26
	v_rcp_f32_e32 v27, v27
	v_add_f32_e32 v28, 1.0, v28
	v_add_f32_e32 v29, 1.0, v29
	v_rcp_f32_e32 v28, v28
	v_rcp_f32_e32 v29, v29
	v_pk_mul_f32 v[20:21], v[20:21], v[26:27]
	s_nop 0
	v_pk_mul_f32 v[16:17], v[20:21], v[16:17]
	v_add_u32_e32 v20, 0xb0, v150
	v_cvt_pk_bf16_f32 v248, v16, v17
	v_pk_mul_f32 v[16:17], v[22:23], v[28:29]
	s_nop 0
	v_pk_mul_f32 v[16:17], v[16:17], v[18:19]
	v_mul_f32_e32 v18, 0xbfb8aa3b, v14
	v_cvt_pk_bf16_f32 v249, v16, v17
	s_nop 0
	v_mul_f32_e32 v16, 0xbfb8aa3b, v12
	v_mul_f32_e32 v17, 0xbfb8aa3b, v13
	v_exp_f32_e32 v16, v16
	v_exp_f32_e32 v17, v17
	v_mul_f32_e32 v19, 0xbfb8aa3b, v15
	v_exp_f32_e32 v18, v18
	v_exp_f32_e32 v19, v19
	v_add_f32_e32 v16, 1.0, v16
	v_add_f32_e32 v17, 1.0, v17
	v_rcp_f32_e32 v16, v16
	v_rcp_f32_e32 v17, v17
	v_add_f32_e32 v18, 1.0, v18
	v_add_f32_e32 v19, 1.0, v19
	v_rcp_f32_e32 v18, v18
	v_rcp_f32_e32 v19, v19
	v_pk_mul_f32 v[12:13], v[12:13], v[16:17]
	s_nop 0
	v_pk_mul_f32 v[8:9], v[12:13], v[8:9]
	v_pk_mul_f32 v[12:13], v[14:15], v[18:19]
	v_cvt_pk_bf16_f32 v250, v8, v9
	v_mul_f32_e32 v9, 0xbfb8aa3b, v4
	v_pk_mul_f32 v[10:11], v[12:13], v[10:11]
	v_exp_f32_e32 v12, v9
	v_mul_f32_e32 v9, 0xbfb8aa3b, v5
	v_exp_f32_e32 v13, v9
	v_cvt_pk_bf16_f32 v251, v10, v11
	v_add_f32_e32 v10, 1.0, v12
	v_mul_f32_e32 v12, 0xbfb8aa3b, v6
	v_add_f32_e32 v11, 1.0, v13
	v_mul_f32_e32 v13, 0xbfb8aa3b, v7
	v_exp_f32_e32 v12, v12
	v_exp_f32_e32 v13, v13
	v_rcp_f32_e32 v10, v10
	v_rcp_f32_e32 v11, v11
	v_add_f32_e32 v12, 1.0, v12
	v_add_f32_e32 v13, 1.0, v13
	v_rcp_f32_e32 v12, v12
	v_rcp_f32_e32 v13, v13
	v_pk_mul_f32 v[4:5], v[4:5], v[10:11]
	s_nop 0
	v_pk_mul_f32 v[0:1], v[4:5], v[0:1]
	s_nop 0
	v_cvt_pk_bf16_f32 v252, v0, v1
	v_pk_mul_f32 v[0:1], v[6:7], v[12:13]
	s_nop 0
	v_pk_mul_f32 v[0:1], v[0:1], v[2:3]
	s_nop 0
	v_cvt_pk_bf16_f32 v253, v0, v1
	s_nop 0
	s_mov_b32 s77, 0
	s_cbranch_vccnz .LBB0_710
	s_andn2_b64 vcc, exec, s[6:7]
	s_cbranch_vccnz .LBB0_709
	s_barrier
	s_branch .LBB0_709
.Lds7_0_a:
	s_add_u32 s82, s8, 0x2c000
	s_addc_u32 s83, s9, 0
	global_store_dwordx4 v229, v[230:233], s[82:83]
	s_mov_b32 s77, 1
	s_branch .Lds7_0_ret
.Lds7_0_b:
	s_add_u32 s82, s8, 0xdc000
	s_addc_u32 s83, s9, 0
	global_store_dwordx4 v229, v[246:249], s[82:83]
	s_mov_b32 s77, 5
	s_branch .Lds7_0_ret
.Lds7_1_a:
	s_add_u32 s82, s8, 0x42000
	s_addc_u32 s83, s9, 0
	global_store_dwordx4 v229, v[234:237], s[82:83]
	s_mov_b32 s77, 2
	s_branch .Lds7_1_ret
.Lds7_1_b:
	s_add_u32 s82, s8, 0xf2000
	s_addc_u32 s83, s9, 0
	global_store_dwordx4 v229, v[250:253], s[82:83]
	s_mov_b32 s77, 6
	s_branch .Lds7_1_ret
.Lds7_2_a:
	s_add_u32 s82, s8, 0xb0000
	s_addc_u32 s83, s9, 0
	global_store_dwordx4 v229, v[238:241], s[82:83]
	s_mov_b32 s77, 3
	s_branch .Lds7_2_ret
.Lds7_3_a:
	s_add_u32 s82, s8, 0xc6000
	s_addc_u32 s83, s9, 0
	global_store_dwordx4 v229, v[242:245], s[82:83]
	s_mov_b32 s77, 4
	s_branch .Lds7_3_ret
.LBB0_720:
	s_add_u32 s82, s8, 0x2c000
	s_addc_u32 s83, s9, 0
	global_store_dwordx4 v229, v[230:233], s[82:83]
	s_add_u32 s82, s8, 0x42000
	s_addc_u32 s83, s9, 0
	global_store_dwordx4 v229, v[234:237], s[82:83]
	s_add_u32 s82, s8, 0xb0000
	s_addc_u32 s83, s9, 0
	global_store_dwordx4 v229, v[238:241], s[82:83]
	s_add_u32 s82, s8, 0xc6000
	s_addc_u32 s83, s9, 0
	global_store_dwordx4 v229, v[242:245], s[82:83]
	s_add_u32 s82, s8, 0xdc000
	s_addc_u32 s83, s9, 0
	global_store_dwordx4 v229, v[246:249], s[82:83]
	s_add_u32 s82, s8, 0xf2000
	s_addc_u32 s83, s9, 0
	global_store_dwordx4 v229, v[250:253], s[82:83]
	s_waitcnt vmcnt(0)
	s_barrier

; #define PG8_STAGE(bufoff, gbase, voff) do { _Pragma("unroll") for (int _i = 0; _i < 2; ++_i) \
;         __builtin_amdgcn_global_load_lds((const unsigned*)((const char*)(gbase) + (voff)[_i]), (PG8_LAS unsigned*)(lds + (bufoff) + ldsw + _i * 8192), 16, 0, 0); } while (0)
; #define PG8_WAIT_V(n) asm volatile("s_waitcnt vmcnt(" #n ")" ::: "memory")
; #define PG8_BAR __builtin_amdgcn_s_barrier()
; template <class Epi, class Sched, bool ALIGN_EPI = false, bool SP2 = false>
; __device__ __forceinline__ void gemm_phase(PG8_LAS unsigned char* lds, const Gemm g, const Sched& S, const Epi& E) {
;     ...
;     const unsigned ldsw = (unsigned)wid * 1024u;
;     const int aoff = lds_byte(wr * 64 + fr, fq * 8), boff = lds_byte(wc * 32 + fr, fq * 8);
;     ...
;         PG8_WAIT_V(2); PG8_BAR;
;         PG8_STAGE(PG8_SB(1, 0), cB + kstep, voffB); PG8_STAGE(PG8_SA(1, 0), cA + kstep, voffA); PG8_STAGE(PG8_SB(1, 1), cB + hstep + kstep, voffB);
;         PG8_WAIT_V(6); PG8_BAR;
.LBB0_1336:
	s_add_u32 s8, s28, 0xfa00000
	s_addc_u32 s9, s29, 0
	s_lshl_b32 s10, s10, 5
	s_and_b32 s18, s10, 0x60
	s_mov_b64 s[10:11], 0x80
	s_add_i32 m0, s25, 0x18000
	v_lshl_add_u64 v[6:7], v[6:7], 0, s[10:11]
	s_ashr_i32 s51, s3, 31
	s_lshl_b32 s13, s12, 13
	s_lshl_b32 s19, s18, 7
	s_waitcnt vmcnt(2)
	s_barrier
	global_load_lds_dwordx4 v[6:7], off
	v_lshl_add_u64 v[4:5], v[4:5], 0, s[10:11]
	s_add_i32 m0, s25, 0x1a000
	s_add_i32 s52, s25, 0x8000
	s_add_i32 s53, s25, 0xa000
	global_load_lds_dwordx4 v[4:5], off
	v_lshl_add_u64 v[0:1], v[0:1], 0, s[10:11]
	s_mov_b32 m0, s52
	s_add_u32 s14, s38, 0x40080
	global_load_lds_dwordx4 v[0:1], off
	v_lshl_add_u64 v[0:1], v[2:3], 0, s[10:11]
	s_mov_b32 m0, s53
	s_addc_u32 s15, s39, 0
	global_load_lds_dwordx4 v[0:1], off
	s_add_i32 m0, s25, 0x1c000
	v_lshl_add_u64 v[0:1], s[14:15], 0, v[130:131]
	global_load_lds_dwordx4 v[0:1], off
	v_lshl_add_u64 v[0:1], s[14:15], 0, v[134:135]
	s_add_i32 m0, s25, 0x1e000
	s_sext_i32_i16 s57, s0
	global_load_lds_dwordx4 v[0:1], off
	v_and_b32_e32 v0, 15, v152
	v_lshlrev_b32_e32 v1, 1, v11
	v_lshlrev_b32_e32 v2, 6, v152
	s_movk_i32 s0, 0x3c0
	v_lshlrev_b32_e32 v3, 2, v152
	v_and_or_b32 v2, v2, s0, v1
	v_and_b32_e32 v3, 32, v3
	v_lshl_or_b32 v144, s12, 6, v0
	v_lshl_or_b32 v0, v0, 6, v1
	v_lshlrev_b32_e32 v1, 8, v152
	v_bitop3_b32 v145, s19, v2, v3 bitop3:0xf6
	v_and_b32_e32 v1, 0x38000, v1
	v_lshlrev_b32_e32 v2, 11, v10
	v_or3_b32 v1, v8, v1, v2
	v_add_u32_e32 v136, v1, v9
	v_lshlrev_b32_e32 v1, 4, v12
	s_waitcnt vmcnt(6)
	s_cmpk_lt_u32 s1, 0x100
	v_and_b32_e32 v1, 0x78000, v1
	v_bitop3_b32 v0, v0, s13, v3 bitop3:0xde
	s_cselect_b64 s[12:13], -1, 0
	v_or3_b32 v1, v8, v1, v2
	s_add_i32 s54, 0, 0x10000
	s_add_i32 s55, 0, 0x14000
	v_or_b32_e32 v146, s18, v11
	v_mov_b32_e32 v137, v131
	v_add_u32_e32 v138, v1, v9
	v_mov_b32_e32 v139, v131
	v_mov_b64_e32 v[140:141], 0x1600
	v_mov_b64_e32 v[142:143], 0x15ff
	v_add_u32_e32 v147, s54, v145
	v_add_u32_e32 v148, s55, v145
	v_add_u32_e32 v149, 0, v0
	s_movk_i32 s56, 0x1600
	s_barrier
	s_mov_b32 s77, 6
	s_branch .LBB0_1339

; #define PG8_STAGE(bufoff, gbase, voff) do { _Pragma("unroll") for (int _i = 0; _i < 2; ++_i) \
;         __builtin_amdgcn_global_load_lds((const unsigned*)((const char*)(gbase) + (voff)[_i]), (PG8_LAS unsigned*)(lds + (bufoff) + ldsw + _i * 8192), 16, 0, 0); } while (0)
; #define PG8_LDA(dst, b, h) do { _Pragma("unroll") for (int m = 0; m < 4; ++m) _Pragma("unroll") for (int k = 0; k < 2; ++k) dst[m][k] = *(const PG8_LAS bf16x8*)(lds + PG8_SA(b, h) + aoff + m * 2048 + k * 1024); } while (0)
; #define PG8_LDB(dst, b, h) do { _Pragma("unroll") for (int n = 0; n < 2; ++n) _Pragma("unroll") for (int k = 0; k < 2; ++k) dst[n][k] = *(const PG8_LAS bf16x8*)(lds + PG8_SB(b, h) + boff + n * 2048 + k * 1024); } while (0)
; #define PG8_MMA(ai, bj, At, Bt) do { __builtin_amdgcn_s_setprio(1); _Pragma("unroll") for (int m = 0; m < 4; ++m) _Pragma("unroll") for (int n = 0; n < 2; ++n) _Pragma("unroll") for (int k = 0; k < 2; ++k) \
;         acc[ai][bj][m][n] = __builtin_amdgcn_mfma_f32_16x16x32_bf16(Bt[n][k], At[m][k], acc[ai][bj][m][n], 0, 0, 0); __builtin_amdgcn_s_setprio(0); } while (0)
; #define PG8_WAIT_V(n) asm volatile("s_waitcnt vmcnt(" #n ")" ::: "memory")
; #define PG8_WAIT_L(n) asm volatile("s_waitcnt lgkmcnt(" #n ")" ::: "memory")
; #define PG8_BAR __builtin_amdgcn_s_barrier()
; #define PG8_SCHED __builtin_amdgcn_sched_barrier(0)
; template <class Epi, class Sched, bool ALIGN_EPI = false, bool SP2 = false>
; __device__ __forceinline__ void gemm_phase(PG8_LAS unsigned char* lds, const Gemm g, const Sched& S, const Epi& E) {
;     ...
;             PG8_LDB(B0, 0, 0); PG8_LDB(B1, 0, 1); PG8_SCHED; PG8_LDA(At, 0, 0); PG8_STAGE(PG8_SA(1, 1), a1 + hstep, voffA);
;             PG8_WAIT_V(8); PG8_WAIT_L(0); PG8_BAR; PG8_MMA(0, 0, At, B0); PG8_MMA(0, 1, At, B1); PG8_BAR; PG8_SCHED;
;             PG8_LDA(At, 0, 1); PG8_STAGE(PG8_SB(0, 0), b2, voffB); PG8_STAGE(PG8_SB(0, 1), b2 + hstep, voffB); PG8_STAGE(PG8_SA(0, 0), a2, voffA);
.LBB0_1342:
	ds_read_b128 v[154:157], v147
	ds_read_b128 v[158:161], v147 offset:1024
	ds_read_b128 v[162:165], v147 offset:2048
	ds_read_b128 v[166:169], v147 offset:3072
	ds_read_b128 v[170:173], v148
	ds_read_b128 v[174:177], v148 offset:1024
	ds_read_b128 v[178:181], v148 offset:2048
	ds_read_b128 v[182:185], v148 offset:3072
	s_add_u32 s33, s36, 0xfffc0080
	s_addc_u32 s34, s37, -1
	s_cmp_eq_u32 s62, 12
	s_cselect_b32 s41, s19, s34
	s_cselect_b32 s40, s58, s33
	s_cselect_b32 s39, s15, s61
	s_cselect_b32 s38, s59, s60
	v_lshl_add_u64 v[150:151], s[36:37], 0, v[136:137]
	s_add_i32 m0, s25, 0xc000
	ds_read_b128 v[186:189], v149
	ds_read_b128 v[190:193], v149 offset:1024
	ds_read_b128 v[194:197], v149 offset:2048
	ds_read_b128 v[198:201], v149 offset:3072
	ds_read_b128 v[202:205], v149 offset:4096
	ds_read_b128 v[206:209], v149 offset:5120
	ds_read_b128 v[210:213], v149 offset:6144
	ds_read_b128 v[214:217], v149 offset:7168
	global_load_lds_dwordx4 v[150:151], off
	v_lshl_add_u64 v[150:151], s[36:37], 0, v[138:139]
	s_add_i32 m0, s25, 0xe000
	s_nop 0
	global_load_lds_dwordx4 v[150:151], off
	s_cmp_eq_u32 s77, 0
	s_cbranch_scc1 .Lds15_0_a
	s_cmp_eq_u32 s77, 4
	s_cbranch_scc1 .Lds15_0_b
.Lds15_0_ret:
	s_waitcnt vmcnt(8)
	s_waitcnt lgkmcnt(0)
	s_barrier
	s_setprio 1
	s_waitcnt lgkmcnt(0)
	v_mfma_f32_16x16x32_bf16 v[124:127], v[154:157], v[186:189], v[124:127]
	v_mfma_f32_16x16x32_bf16 v[116:119], v[162:165], v[186:189], v[116:119]
	v_mfma_f32_16x16x32_bf16 v[108:111], v[154:157], v[194:197], v[108:111]
	v_mfma_f32_16x16x32_bf16 v[100:103], v[162:165], v[194:197], v[100:103]
	v_mfma_f32_16x16x32_bf16 v[92:95], v[154:157], v[202:205], v[92:95]
	v_mfma_f32_16x16x32_bf16 v[84:87], v[162:165], v[202:205], v[84:87]
	v_mfma_f32_16x16x32_bf16 v[76:79], v[154:157], v[210:213], v[76:79]
	v_mfma_f32_16x16x32_bf16 v[68:71], v[162:165], v[210:213], v[68:71]
	v_mfma_f32_16x16x32_bf16 v[124:127], v[158:161], v[190:193], v[124:127]
	v_mfma_f32_16x16x32_bf16 v[116:119], v[166:169], v[190:193], v[116:119]
	v_mfma_f32_16x16x32_bf16 v[108:111], v[158:161], v[198:201], v[108:111]
	v_mfma_f32_16x16x32_bf16 v[100:103], v[166:169], v[198:201], v[100:103]
	v_mfma_f32_16x16x32_bf16 v[92:95], v[158:161], v[206:209], v[92:95]
	v_mfma_f32_16x16x32_bf16 v[84:87], v[166:169], v[206:209], v[84:87]
	v_mfma_f32_16x16x32_bf16 v[76:79], v[158:161], v[214:217], v[76:79]
	v_mfma_f32_16x16x32_bf16 v[68:71], v[166:169], v[214:217], v[68:71]
	s_setprio 0
	s_setprio 1
	v_mfma_f32_16x16x32_bf16 v[120:123], v[170:173], v[186:189], v[120:123]
	v_mfma_f32_16x16x32_bf16 v[112:115], v[178:181], v[186:189], v[112:115]
	v_mfma_f32_16x16x32_bf16 v[104:107], v[170:173], v[194:197], v[104:107]
	v_mfma_f32_16x16x32_bf16 v[96:99], v[178:181], v[194:197], v[96:99]
	v_mfma_f32_16x16x32_bf16 v[88:91], v[170:173], v[202:205], v[88:91]
	v_mfma_f32_16x16x32_bf16 v[80:83], v[178:181], v[202:205], v[80:83]
	v_mfma_f32_16x16x32_bf16 v[72:75], v[170:173], v[210:213], v[72:75]
	v_mfma_f32_16x16x32_bf16 v[64:67], v[178:181], v[210:213], v[64:67]
	v_mfma_f32_16x16x32_bf16 v[120:123], v[174:177], v[190:193], v[120:123]
	v_mfma_f32_16x16x32_bf16 v[112:115], v[182:185], v[190:193], v[112:115]
	v_mfma_f32_16x16x32_bf16 v[104:107], v[174:177], v[198:201], v[104:107]
	v_mfma_f32_16x16x32_bf16 v[96:99], v[182:185], v[198:201], v[96:99]
	v_mfma_f32_16x16x32_bf16 v[88:91], v[174:177], v[206:209], v[88:91]
	v_mfma_f32_16x16x32_bf16 v[80:83], v[182:185], v[206:209], v[80:83]
	v_mfma_f32_16x16x32_bf16 v[72:75], v[174:177], v[214:217], v[72:75]
	v_mfma_f32_16x16x32_bf16 v[64:67], v[182:185], v[214:217], v[64:67]
	s_setprio 0
	s_barrier
	s_add_i32 s33, s54, s44
	v_lshl_add_u64 v[150:151], s[38:39], 0, v[130:131]
	s_mov_b32 m0, s33
	ds_read_b128 v[186:189], v149 offset:16384
	ds_read_b128 v[190:193], v149 offset:17408
	ds_read_b128 v[194:197], v149 offset:18432
	ds_read_b128 v[198:201], v149 offset:19456
	ds_read_b128 v[202:205], v149 offset:20480
	ds_read_b128 v[206:209], v149 offset:21504
	ds_read_b128 v[210:213], v149 offset:22528
	ds_read_b128 v[214:217], v149 offset:23552
	global_load_lds_dwordx4 v[150:151], off
	s_add_i32 m0, s33, 0x2000
	s_add_u32 s64, s38, 0x40000
	v_lshl_add_u64 v[218:219], s[38:39], 0, v[134:135]
	s_addc_u32 s65, s39, 0
	s_add_i32 s33, s55, s44
	global_load_lds_dwordx4 v[218:219], off
	v_lshl_add_u64 v[220:221], s[64:65], 0, v[130:131]
	s_mov_b32 m0, s33
	v_lshl_add_u64 v[222:223], s[40:41], 0, v[132:133]
	global_load_lds_dwordx4 v[220:221], off
	v_lshl_add_u64 v[220:221], s[64:65], 0, v[134:135]
	s_add_i32 m0, s33, 0x2000
	s_nop 0
	global_load_lds_dwordx4 v[220:221], off
	v_lshl_add_u64 v[220:221], s[40:41], 0, v[128:129]
	s_mov_b32 m0, s25
	s_nop 0
	global_load_lds_dwordx4 v[220:221], off
	s_mov_b32 m0, s47
	s_nop 0
	global_load_lds_dwordx4 v[222:223], off
	s_cmp_eq_u32 s77, 1
	s_cbranch_scc1 .Lds15_1_a
	s_cmp_eq_u32 s77, 5
	s_cbranch_scc1 .Lds15_1_b
; #define PG8_STAGE(bufoff, gbase, voff) do { _Pragma("unroll") for (int _i = 0; _i < 2; ++_i) \
;         __builtin_amdgcn_global_load_lds((const unsigned*)((const char*)(gbase) + (voff)[_i]), (PG8_LAS unsigned*)(lds + (bufoff) + ldsw + _i * 8192), 16, 0, 0); } while (0)
; #define PG8_LDA(dst, b, h) do { _Pragma("unroll") for (int m = 0; m < 4; ++m) _Pragma("unroll") for (int k = 0; k < 2; ++k) dst[m][k] = *(const PG8_LAS bf16x8*)(lds + PG8_SA(b, h) + aoff + m * 2048 + k * 1024); } while (0)
; #define PG8_LDB(dst, b, h) do { _Pragma("unroll") for (int n = 0; n < 2; ++n) _Pragma("unroll") for (int k = 0; k < 2; ++k) dst[n][k] = *(const PG8_LAS bf16x8*)(lds + PG8_SB(b, h) + boff + n * 2048 + k * 1024); } while (0)
; #define PG8_MMA(ai, bj, At, Bt) do { __builtin_amdgcn_s_setprio(1); _Pragma("unroll") for (int m = 0; m < 4; ++m) _Pragma("unroll") for (int n = 0; n < 2; ++n) _Pragma("unroll") for (int k = 0; k < 2; ++k) \
;         acc[ai][bj][m][n] = __builtin_amdgcn_mfma_f32_16x16x32_bf16(Bt[n][k], At[m][k], acc[ai][bj][m][n], 0, 0, 0); __builtin_amdgcn_s_setprio(0); } while (0)
; #define PG8_WAIT_V(n) asm volatile("s_waitcnt vmcnt(" #n ")" ::: "memory")
; #define PG8_WAIT_L(n) asm volatile("s_waitcnt lgkmcnt(" #n ")" ::: "memory")
; #define PG8_BAR __builtin_amdgcn_s_barrier()
; #define PG8_SCHED __builtin_amdgcn_sched_barrier(0)
; template <class Epi, class Sched, bool ALIGN_EPI = false, bool SP2 = false>
; __device__ __forceinline__ void gemm_phase(PG8_LAS unsigned char* lds, const Gemm g, const Sched& S, const Epi& E) {
;     ...
;             PG8_LDA(At, 0, 1); PG8_STAGE(PG8_SB(0, 0), b2, voffB); PG8_STAGE(PG8_SB(0, 1), b2 + hstep, voffB); PG8_STAGE(PG8_SA(0, 0), a2, voffA);
;             PG8_WAIT_V(8); PG8_WAIT_L(0); PG8_BAR; PG8_MMA(1, 0, At, B0); PG8_MMA(1, 1, At, B1); PG8_BAR; PG8_SCHED;
;             PG8_LDB(B0, 1, 0); PG8_LDB(B1, 1, 1); PG8_SCHED; PG8_LDA(At, 1, 0); PG8_STAGE(PG8_SA(0, 1), a2 + hstep, voffA);
.Lds15_1_ret:
	s_waitcnt vmcnt(8)
	s_waitcnt lgkmcnt(0)
	s_barrier
	s_setprio 1
	s_waitcnt lgkmcnt(0)
	v_mfma_f32_16x16x32_bf16 v[60:63], v[154:157], v[186:189], v[60:63]
	v_mfma_f32_16x16x32_bf16 v[52:55], v[162:165], v[186:189], v[52:55]
	v_mfma_f32_16x16x32_bf16 v[44:47], v[154:157], v[194:197], v[44:47]
	v_mfma_f32_16x16x32_bf16 v[36:39], v[162:165], v[194:197], v[36:39]
	v_mfma_f32_16x16x32_bf16 v[28:31], v[154:157], v[202:205], v[28:31]
	v_mfma_f32_16x16x32_bf16 v[20:23], v[162:165], v[202:205], v[20:23]
	v_mfma_f32_16x16x32_bf16 v[12:15], v[154:157], v[210:213], v[12:15]
	v_mfma_f32_16x16x32_bf16 v[4:7], v[162:165], v[210:213], v[4:7]
	v_mfma_f32_16x16x32_bf16 v[60:63], v[158:161], v[190:193], v[60:63]
	v_mfma_f32_16x16x32_bf16 v[52:55], v[166:169], v[190:193], v[52:55]
	v_mfma_f32_16x16x32_bf16 v[44:47], v[158:161], v[198:201], v[44:47]
	v_mfma_f32_16x16x32_bf16 v[36:39], v[166:169], v[198:201], v[36:39]
	v_mfma_f32_16x16x32_bf16 v[28:31], v[158:161], v[206:209], v[28:31]
	v_mfma_f32_16x16x32_bf16 v[20:23], v[166:169], v[206:209], v[20:23]
	v_mfma_f32_16x16x32_bf16 v[12:15], v[158:161], v[214:217], v[12:15]
	v_mfma_f32_16x16x32_bf16 v[4:7], v[166:169], v[214:217], v[4:7]
	s_setprio 0
	s_setprio 1
	v_mfma_f32_16x16x32_bf16 v[56:59], v[170:173], v[186:189], v[56:59]
	v_mfma_f32_16x16x32_bf16 v[48:51], v[178:181], v[186:189], v[48:51]
	v_mfma_f32_16x16x32_bf16 v[40:43], v[170:173], v[194:197], v[40:43]
	v_mfma_f32_16x16x32_bf16 v[32:35], v[178:181], v[194:197], v[32:35]
	v_mfma_f32_16x16x32_bf16 v[24:27], v[170:173], v[202:205], v[24:27]
	v_mfma_f32_16x16x32_bf16 v[16:19], v[178:181], v[202:205], v[16:19]
	v_mfma_f32_16x16x32_bf16 v[8:11], v[170:173], v[210:213], v[8:11]
	v_mfma_f32_16x16x32_bf16 v[0:3], v[178:181], v[210:213], v[0:3]
	v_mfma_f32_16x16x32_bf16 v[56:59], v[174:177], v[190:193], v[56:59]
	v_mfma_f32_16x16x32_bf16 v[48:51], v[182:185], v[190:193], v[48:51]
	v_mfma_f32_16x16x32_bf16 v[40:43], v[174:177], v[198:201], v[40:43]
	v_mfma_f32_16x16x32_bf16 v[32:35], v[182:185], v[198:201], v[32:35]
	v_mfma_f32_16x16x32_bf16 v[24:27], v[174:177], v[206:209], v[24:27]
	v_mfma_f32_16x16x32_bf16 v[16:19], v[182:185], v[206:209], v[16:19]
	v_mfma_f32_16x16x32_bf16 v[8:11], v[174:177], v[214:217], v[8:11]
	v_mfma_f32_16x16x32_bf16 v[0:3], v[182:185], v[214:217], v[0:3]
	s_setprio 0
	s_barrier
	s_add_i32 s33, 0, 0x18000
	v_add_u32_e32 v153, s33, v145
	s_add_i32 s34, 0, 0x1c000
	ds_read_b128 v[154:157], v153
	ds_read_b128 v[158:161], v153 offset:1024
	ds_read_b128 v[162:165], v153 offset:2048
	ds_read_b128 v[166:169], v153 offset:3072
	v_add_u32_e32 v153, s34, v145
	ds_read_b128 v[170:173], v153
	ds_read_b128 v[174:177], v153 offset:1024
	ds_read_b128 v[178:181], v153 offset:2048
	ds_read_b128 v[182:185], v153 offset:3072
	s_add_u32 s40, s40, 0x40000
	s_addc_u32 s41, s41, 0
	s_mov_b32 m0, s48
	v_lshl_add_u64 v[224:225], s[40:41], 0, v[128:129]
	ds_read_b128 v[186:189], v149 offset:32768
	ds_read_b128 v[190:193], v149 offset:33792
	ds_read_b128 v[194:197], v149 offset:34816
	ds_read_b128 v[198:201], v149 offset:35840
	ds_read_b128 v[202:205], v149 offset:36864
	ds_read_b128 v[206:209], v149 offset:37888
	ds_read_b128 v[210:213], v149 offset:38912
	ds_read_b128 v[214:217], v149 offset:39936
	global_load_lds_dwordx4 v[224:225], off
	v_lshl_add_u64 v[224:225], s[40:41], 0, v[132:133]
	s_mov_b32 m0, s49
	s_nop 0
	global_load_lds_dwordx4 v[224:225], off
	s_cmp_eq_u32 s77, 2
	s_cbranch_scc1 .Lds15_2_a
.Lds15_2_ret:
	s_waitcnt vmcnt(8)
	s_waitcnt lgkmcnt(0)
	s_barrier
	s_setprio 1
	s_waitcnt lgkmcnt(0)
	v_mfma_f32_16x16x32_bf16 v[124:127], v[154:157], v[186:189], v[124:127]
	v_mfma_f32_16x16x32_bf16 v[116:119], v[162:165], v[186:189], v[116:119]
	v_mfma_f32_16x16x32_bf16 v[108:111], v[154:157], v[194:197], v[108:111]
	v_mfma_f32_16x16x32_bf16 v[100:103], v[162:165], v[194:197], v[100:103]
	v_mfma_f32_16x16x32_bf16 v[92:95], v[154:157], v[202:205], v[92:95]
	v_mfma_f32_16x16x32_bf16 v[84:87], v[162:165], v[202:205], v[84:87]
	v_mfma_f32_16x16x32_bf16 v[76:79], v[154:157], v[210:213], v[76:79]
	v_mfma_f32_16x16x32_bf16 v[68:71], v[162:165], v[210:213], v[68:71]
	v_mfma_f32_16x16x32_bf16 v[124:127], v[158:161], v[190:193], v[124:127]
	v_mfma_f32_16x16x32_bf16 v[116:119], v[166:169], v[190:193], v[116:119]
	v_mfma_f32_16x16x32_bf16 v[108:111], v[158:161], v[198:201], v[108:111]
	v_mfma_f32_16x16x32_bf16 v[100:103], v[166:169], v[198:201], v[100:103]
	v_mfma_f32_16x16x32_bf16 v[92:95], v[158:161], v[206:209], v[92:95]
	v_mfma_f32_16x16x32_bf16 v[84:87], v[166:169], v[206:209], v[84:87]
	v_mfma_f32_16x16x32_bf16 v[76:79], v[158:161], v[214:217], v[76:79]
	v_mfma_f32_16x16x32_bf16 v[68:71], v[166:169], v[214:217], v[68:71]
	s_setprio 0
	s_setprio 1
	v_mfma_f32_16x16x32_bf16 v[120:123], v[170:173], v[186:189], v[120:123]
	v_mfma_f32_16x16x32_bf16 v[112:115], v[178:181], v[186:189], v[112:115]
	v_mfma_f32_16x16x32_bf16 v[104:107], v[170:173], v[194:197], v[104:107]
	v_mfma_f32_16x16x32_bf16 v[96:99], v[178:181], v[194:197], v[96:99]
	v_mfma_f32_16x16x32_bf16 v[88:91], v[170:173], v[202:205], v[88:91]
	v_mfma_f32_16x16x32_bf16 v[80:83], v[178:181], v[202:205], v[80:83]
	v_mfma_f32_16x16x32_bf16 v[72:75], v[170:173], v[210:213], v[72:75]
	v_mfma_f32_16x16x32_bf16 v[64:67], v[178:181], v[210:213], v[64:67]
	v_mfma_f32_16x16x32_bf16 v[120:123], v[174:177], v[190:193], v[120:123]
	v_mfma_f32_16x16x32_bf16 v[112:115], v[182:185], v[190:193], v[112:115]
	v_mfma_f32_16x16x32_bf16 v[104:107], v[174:177], v[198:201], v[104:107]
	v_mfma_f32_16x16x32_bf16 v[96:99], v[182:185], v[198:201], v[96:99]
	v_mfma_f32_16x16x32_bf16 v[88:91], v[174:177], v[206:209], v[88:91]
	v_mfma_f32_16x16x32_bf16 v[80:83], v[182:185], v[206:209], v[80:83]
	v_mfma_f32_16x16x32_bf16 v[72:75], v[174:177], v[214:217], v[72:75]
	v_mfma_f32_16x16x32_bf16 v[64:67], v[182:185], v[214:217], v[64:67]
	s_setprio 0
	s_barrier
; __device__ __forceinline__ unsigned pk2(float lo, float hi) { f32x2 v = {lo, hi}; bf16x2_t b = __builtin_convertvector(v, bf16x2_t); return __builtin_bit_cast(unsigned, b); }
; __device__ __forceinline__ float silu_f(float a) { return a * __builtin_amdgcn_rcpf(1.0f + __expf(-a)); }
; #define PG8_STAGE(bufoff, gbase, voff) do { _Pragma("unroll") for (int _i = 0; _i < 2; ++_i) \
;         __builtin_amdgcn_global_load_lds((const unsigned*)((const char*)(gbase) + (voff)[_i]), (PG8_LAS unsigned*)(lds + (bufoff) + ldsw + _i * 8192), 16, 0, 0); } while (0)
; #define PG8_LDA(dst, b, h) do { _Pragma("unroll") for (int m = 0; m < 4; ++m) _Pragma("unroll") for (int k = 0; k < 2; ++k) dst[m][k] = *(const PG8_LAS bf16x8*)(lds + PG8_SA(b, h) + aoff + m * 2048 + k * 1024); } while (0)
; #define PG8_BAR __builtin_amdgcn_s_barrier()
;     __device__ __forceinline__ void operator()(const f32x4 (&acc)[2][2][4][2], const Unit& u, int wr, int wc, int fr, int fq) const {
;         const int row0 = u.pm * BM + wr * 64 + fr; const int col0 = u.pn * HALF + wc * 32 + 8 * fq;
; #pragma unroll
;         for (int ai = 0; ai < 2; ++ai)
; #pragma unroll
;             for (int m = 0; m < 4; ++m) { const int row = row0 + ai * HALF + m * 16;
;                 const f32x4 a0 = acc[ai][0][m][0], a1 = acc[ai][0][m][1], b0 = acc[ai][1][m][0], b1 = acc[ai][1][m][1];
;                 u32x4 w; w.x = pk2(silu_f(a0[0]) * b0[0], silu_f(a0[1]) * b0[1]); w.y = pk2(silu_f(a0[2]) * b0[2], silu_f(a0[3]) * b0[3]);
;                 w.z = pk2(silu_f(a1[0]) * b1[0], silu_f(a1[1]) * b1[1]); w.w = pk2(silu_f(a1[2]) * b1[2], silu_f(a1[3]) * b1[3]);
;                 *(u32x4*)(H + (size_t)row * ldh + col0) = w; }
; template <class Epi, class Sched, bool ALIGN_EPI = false, bool SP2 = false>
; __device__ __forceinline__ void gemm_phase(PG8_LAS unsigned char* lds, const Gemm g, const Sched& S, const Epi& E) {
;     ...
;             PG8_LDB(B0, 1, 0); PG8_LDB(B1, 1, 1); PG8_SCHED; PG8_LDA(At, 1, 0); PG8_STAGE(PG8_SA(0, 1), a2 + hstep, voffA);
;             PG8_WAIT_V(8); PG8_WAIT_L(0); PG8_BAR; PG8_MMA(0, 0, At, B0); PG8_MMA(0, 1, At, B1); PG8_BAR; PG8_SCHED;
;             PG8_LDA(At, 1, 1); PG8_STAGE(PG8_SB(1, 0), b3, voffB); PG8_STAGE(PG8_SB(1, 1), b3 + hstep, voffB); PG8_STAGE(PG8_SA(1, 0), a3, voffA);
;             PG8_WAIT_V(8); PG8_WAIT_L(0); PG8_BAR; PG8_MMA(1, 0, At, B0); PG8_MMA(1, 1, At, B1); PG8_BAR; PG8_SCHED;
	s_add_i32 s33, s33, s44
	v_lshl_add_u64 v[150:151], v[150:151], 0, s[10:11]
	s_mov_b32 m0, s33
	ds_read_b128 v[186:189], v149 offset:49152
	ds_read_b128 v[190:193], v149 offset:50176
	ds_read_b128 v[194:197], v149 offset:51200
	ds_read_b128 v[198:201], v149 offset:52224
	ds_read_b128 v[202:205], v149 offset:53248
	ds_read_b128 v[206:209], v149 offset:54272
	ds_read_b128 v[210:213], v149 offset:55296
	ds_read_b128 v[214:217], v149 offset:56320
	global_load_lds_dwordx4 v[150:151], off
	s_add_i32 m0, s33, 0x2000
	s_add_u32 s38, s38, 0x40080
	v_lshl_add_u64 v[150:151], v[218:219], 0, s[10:11]
	s_addc_u32 s39, s39, 0
	s_add_i32 s33, s34, s44
	global_load_lds_dwordx4 v[150:151], off
	v_lshl_add_u64 v[150:151], s[38:39], 0, v[130:131]
	s_mov_b32 m0, s33
	s_nop 0
	global_load_lds_dwordx4 v[150:151], off
	v_lshl_add_u64 v[150:151], s[38:39], 0, v[134:135]
	s_add_i32 m0, s33, 0x2000
	s_nop 0
	global_load_lds_dwordx4 v[150:151], off
	v_lshl_add_u64 v[150:151], v[220:221], 0, s[10:11]
	s_mov_b32 m0, s52
	s_nop 0
	global_load_lds_dwordx4 v[150:151], off
	v_lshl_add_u64 v[150:151], v[222:223], 0, s[10:11]
	s_mov_b32 m0, s53
	s_nop 0
	global_load_lds_dwordx4 v[150:151], off
	s_cmp_eq_u32 s77, 3
	s_cbranch_scc1 .Lds15_3_a
.Lds15_3_ret:
	s_waitcnt vmcnt(8)
	s_waitcnt lgkmcnt(0)
	s_barrier
	s_setprio 1
	s_waitcnt lgkmcnt(0)
	v_mfma_f32_16x16x32_bf16 v[60:63], v[154:157], v[186:189], v[60:63]
	v_mfma_f32_16x16x32_bf16 v[52:55], v[162:165], v[186:189], v[52:55]
	v_mfma_f32_16x16x32_bf16 v[44:47], v[154:157], v[194:197], v[44:47]
	v_mfma_f32_16x16x32_bf16 v[36:39], v[162:165], v[194:197], v[36:39]
	v_mfma_f32_16x16x32_bf16 v[28:31], v[154:157], v[202:205], v[28:31]
	v_mfma_f32_16x16x32_bf16 v[20:23], v[162:165], v[202:205], v[20:23]
	v_mfma_f32_16x16x32_bf16 v[12:15], v[154:157], v[210:213], v[12:15]
	v_mfma_f32_16x16x32_bf16 v[4:7], v[162:165], v[210:213], v[4:7]
	v_mfma_f32_16x16x32_bf16 v[60:63], v[158:161], v[190:193], v[60:63]
	v_mfma_f32_16x16x32_bf16 v[52:55], v[166:169], v[190:193], v[52:55]
	v_mfma_f32_16x16x32_bf16 v[44:47], v[158:161], v[198:201], v[44:47]
	v_mfma_f32_16x16x32_bf16 v[36:39], v[166:169], v[198:201], v[36:39]
	v_mfma_f32_16x16x32_bf16 v[28:31], v[158:161], v[206:209], v[28:31]
	v_mfma_f32_16x16x32_bf16 v[20:23], v[166:169], v[206:209], v[20:23]
	v_mfma_f32_16x16x32_bf16 v[12:15], v[158:161], v[214:217], v[12:15]
	v_mfma_f32_16x16x32_bf16 v[4:7], v[166:169], v[214:217], v[4:7]
	s_setprio 0
	s_setprio 1
	v_mfma_f32_16x16x32_bf16 v[56:59], v[170:173], v[186:189], v[56:59]
	v_mfma_f32_16x16x32_bf16 v[48:51], v[178:181], v[186:189], v[48:51]
	v_mfma_f32_16x16x32_bf16 v[40:43], v[170:173], v[194:197], v[40:43]
	v_mfma_f32_16x16x32_bf16 v[32:35], v[178:181], v[194:197], v[32:35]
	v_mfma_f32_16x16x32_bf16 v[24:27], v[170:173], v[202:205], v[24:27]
	v_mfma_f32_16x16x32_bf16 v[16:19], v[178:181], v[202:205], v[16:19]
	v_mfma_f32_16x16x32_bf16 v[8:11], v[170:173], v[210:213], v[8:11]
	v_mfma_f32_16x16x32_bf16 v[0:3], v[178:181], v[210:213], v[0:3]
	v_mfma_f32_16x16x32_bf16 v[56:59], v[174:177], v[190:193], v[56:59]
	v_mfma_f32_16x16x32_bf16 v[48:51], v[182:185], v[190:193], v[48:51]
	v_mfma_f32_16x16x32_bf16 v[40:43], v[174:177], v[198:201], v[40:43]
	v_mfma_f32_16x16x32_bf16 v[32:35], v[182:185], v[198:201], v[32:35]
	v_mfma_f32_16x16x32_bf16 v[24:27], v[174:177], v[206:209], v[24:27]
	v_mfma_f32_16x16x32_bf16 v[16:19], v[182:185], v[206:209], v[16:19]
	v_mfma_f32_16x16x32_bf16 v[8:11], v[174:177], v[214:217], v[8:11]
	v_mfma_f32_16x16x32_bf16 v[0:3], v[182:185], v[214:217], v[0:3]
	s_setprio 0
	s_barrier
	s_add_i32 s62, s62, 2
	s_add_u32 s36, s36, 0x100
	s_addc_u32 s37, s37, 0
	s_add_u32 s60, s60, 0x100
	s_addc_u32 s61, s61, 0
	s_cmp_gt_u32 s62, 13
	s_cbranch_scc0 .LBB0_1342
	s_and_b64 vcc, exec, s[12:13]
	s_cbranch_vccz .LBB0_1345
	s_barrier
.LBB0_1345:
	v_mul_f32_e32 v151, 0xbfb8aa3b, v124
	v_exp_f32_e32 v151, v151
	v_mul_f32_e32 v153, 0xbfb8aa3b, v125
	v_exp_f32_e32 v153, v153
	v_mul_f32_e32 v157, 0xbfb8aa3b, v127
	v_add_f32_e32 v151, 1.0, v151
	v_rcp_f32_e32 v156, v151
	v_add_f32_e32 v151, 1.0, v153
	v_mul_f32_e32 v153, 0xbfb8aa3b, v126
	v_exp_f32_e32 v153, v153
	v_exp_f32_e32 v159, v157
	v_rcp_f32_e32 v157, v151
	v_lshl_or_b32 v154, s57, 7, v146
	v_add_f32_e32 v151, 1.0, v153
	v_rcp_f32_e32 v158, v151
	v_add_f32_e32 v151, 1.0, v159
	v_rcp_f32_e32 v159, v151
	v_pk_mul_f32 v[124:125], v[124:125], v[156:157]
	v_lshl_add_u32 v150, s24, 8, v144
	v_pk_mul_f32 v[120:121], v[124:125], v[120:121]
	v_pk_mul_f32 v[124:125], v[126:127], v[158:159]
	v_cvt_pk_bf16_f32 v120, v120, v121
	v_mul_f32_e32 v121, 0xbfb8aa3b, v116
	v_pk_mul_f32 v[122:123], v[124:125], v[122:123]
	v_exp_f32_e32 v124, v121
	v_mul_f32_e32 v121, 0xbfb8aa3b, v117
	v_exp_f32_e32 v125, v121
	v_cvt_pk_bf16_f32 v121, v122, v123
	v_add_f32_e32 v122, 1.0, v124
	v_mul_f32_e32 v124, 0xbfb8aa3b, v118
	v_add_f32_e32 v123, 1.0, v125
	v_mul_f32_e32 v125, 0xbfb8aa3b, v119
	v_exp_f32_e32 v124, v124
	v_exp_f32_e32 v125, v125
	v_rcp_f32_e32 v122, v122
	v_rcp_f32_e32 v123, v123
	v_add_f32_e32 v124, 1.0, v124
	v_add_f32_e32 v125, 1.0, v125
	v_rcp_f32_e32 v124, v124
	v_rcp_f32_e32 v125, v125
	v_pk_mul_f32 v[116:117], v[116:117], v[122:123]
	v_ashrrev_i32_e32 v155, 31, v154
	v_pk_mul_f32 v[112:113], v[116:117], v[112:113]
	s_andn2_b64 vcc, exec, s[0:1]
	v_cvt_pk_bf16_f32 v122, v112, v113
	v_pk_mul_f32 v[112:113], v[118:119], v[124:125]
	v_mul_f32_e32 v118, 0xbfb8aa3b, v110
	v_pk_mul_f32 v[112:113], v[112:113], v[114:115]
	v_lshlrev_b64 v[114:115], 1, v[154:155]
	v_cvt_pk_bf16_f32 v123, v112, v113
	v_mov_b64_e32 v[112:113], s[8:9]
	v_mad_i64_i32 v[116:117], s[36:37], v150, s56, v[112:113]
; __device__ __forceinline__ unsigned pk2(float lo, float hi) { f32x2 v = {lo, hi}; bf16x2_t b = __builtin_convertvector(v, bf16x2_t); return __builtin_bit_cast(unsigned, b); }
; __device__ __forceinline__ float silu_f(float a) { return a * __builtin_amdgcn_rcpf(1.0f + __expf(-a)); }
;     __device__ __forceinline__ void operator()(const f32x4 (&acc)[2][2][4][2], const Unit& u, int wr, int wc, int fr, int fq) const {
;         const int row0 = u.pm * BM + wr * 64 + fr; const int col0 = u.pn * HALF + wc * 32 + 8 * fq;
; #pragma unroll
;         for (int ai = 0; ai < 2; ++ai)
; #pragma unroll
;             for (int m = 0; m < 4; ++m) { const int row = row0 + ai * HALF + m * 16;
;                 const f32x4 a0 = acc[ai][0][m][0], a1 = acc[ai][0][m][1], b0 = acc[ai][1][m][0], b1 = acc[ai][1][m][1];
;                 u32x4 w; w.x = pk2(silu_f(a0[0]) * b0[0], silu_f(a0[1]) * b0[1]); w.y = pk2(silu_f(a0[2]) * b0[2], silu_f(a0[3]) * b0[3]);
;                 w.z = pk2(silu_f(a1[0]) * b1[0], silu_f(a1[1]) * b1[1]); w.w = pk2(silu_f(a1[2]) * b1[2], silu_f(a1[3]) * b1[3]);
;                 *(u32x4*)(H + (size_t)row * ldh + col0) = w; }
	v_lshl_add_u64 v[116:117], v[116:117], 0, v[114:115]
	global_store_dwordx4 v[116:117], v[120:123], off
	v_mad_u32_u24 v229, v150, s56, v114
	v_mul_f32_e32 v116, 0xbfb8aa3b, v108
	v_mul_f32_e32 v117, 0xbfb8aa3b, v109
	v_exp_f32_e32 v116, v116
	v_exp_f32_e32 v117, v117
	v_mul_f32_e32 v119, 0xbfb8aa3b, v111
	v_exp_f32_e32 v118, v118
	v_exp_f32_e32 v119, v119
	v_add_f32_e32 v116, 1.0, v116
	v_add_f32_e32 v117, 1.0, v117
	v_rcp_f32_e32 v116, v116
	v_rcp_f32_e32 v117, v117
	v_add_f32_e32 v118, 1.0, v118
	v_add_f32_e32 v119, 1.0, v119
	v_rcp_f32_e32 v118, v118
	v_rcp_f32_e32 v119, v119
	v_pk_mul_f32 v[108:109], v[108:109], v[116:117]
	v_or_b32_e32 v120, 16, v150
	v_pk_mul_f32 v[104:105], v[108:109], v[104:105]
	v_pk_mul_f32 v[108:109], v[110:111], v[118:119]
	v_cvt_pk_bf16_f32 v104, v104, v105
	v_mul_f32_e32 v105, 0xbfb8aa3b, v100
	v_pk_mul_f32 v[106:107], v[108:109], v[106:107]
	v_exp_f32_e32 v108, v105
	v_mul_f32_e32 v105, 0xbfb8aa3b, v101
	v_exp_f32_e32 v109, v105
	v_cvt_pk_bf16_f32 v105, v106, v107
	v_add_f32_e32 v106, 1.0, v108
	v_mul_f32_e32 v108, 0xbfb8aa3b, v102
	v_add_f32_e32 v107, 1.0, v109
	v_mul_f32_e32 v109, 0xbfb8aa3b, v103
	v_exp_f32_e32 v108, v108
	v_exp_f32_e32 v109, v109
	v_rcp_f32_e32 v106, v106
	v_rcp_f32_e32 v107, v107
	v_add_f32_e32 v108, 1.0, v108
	v_add_f32_e32 v109, 1.0, v109
	v_rcp_f32_e32 v108, v108
	v_rcp_f32_e32 v109, v109
	v_pk_mul_f32 v[100:101], v[100:101], v[106:107]
	s_mov_b64 s[0:1], -1
	v_pk_mul_f32 v[96:97], v[100:101], v[96:97]
	v_or_b32_e32 v100, 32, v150
	v_cvt_pk_bf16_f32 v106, v96, v97
	v_pk_mul_f32 v[96:97], v[102:103], v[108:109]
	s_nop 0
	v_pk_mul_f32 v[96:97], v[96:97], v[98:99]
	v_mul_f32_e32 v98, 0xbfb8aa3b, v94
	v_cvt_pk_bf16_f32 v107, v96, v97
	v_mad_i64_i32 v[96:97], s[36:37], v120, s56, v[112:113]
	v_lshl_add_u64 v[96:97], v[96:97], 0, v[114:115]
	global_store_dwordx4 v[96:97], v[104:107], off
	v_mul_f32_e32 v96, 0xbfb8aa3b, v92
	v_mul_f32_e32 v97, 0xbfb8aa3b, v93
	v_exp_f32_e32 v96, v96
	v_exp_f32_e32 v97, v97
	v_mul_f32_e32 v99, 0xbfb8aa3b, v95
	v_exp_f32_e32 v98, v98
	v_exp_f32_e32 v99, v99
	v_add_f32_e32 v96, 1.0, v96
	v_add_f32_e32 v97, 1.0, v97
	v_rcp_f32_e32 v96, v96
	v_rcp_f32_e32 v97, v97
	v_add_f32_e32 v98, 1.0, v98
	v_add_f32_e32 v99, 1.0, v99
	v_rcp_f32_e32 v98, v98
	v_rcp_f32_e32 v99, v99
	v_pk_mul_f32 v[92:93], v[92:93], v[96:97]
	s_nop 0
	v_pk_mul_f32 v[88:89], v[92:93], v[88:89]
	v_pk_mul_f32 v[92:93], v[94:95], v[98:99]
	v_cvt_pk_bf16_f32 v230, v88, v89
	v_mul_f32_e32 v89, 0xbfb8aa3b, v84
	v_pk_mul_f32 v[90:91], v[92:93], v[90:91]
	v_exp_f32_e32 v92, v89
	v_mul_f32_e32 v89, 0xbfb8aa3b, v85
	v_exp_f32_e32 v93, v89
	v_cvt_pk_bf16_f32 v231, v90, v91
	v_add_f32_e32 v90, 1.0, v92
	v_mul_f32_e32 v92, 0xbfb8aa3b, v86
	v_add_f32_e32 v91, 1.0, v93
	v_mul_f32_e32 v93, 0xbfb8aa3b, v87
	v_exp_f32_e32 v92, v92
	v_exp_f32_e32 v93, v93
	v_rcp_f32_e32 v90, v90
	v_rcp_f32_e32 v91, v91
	v_add_f32_e32 v92, 1.0, v92
	v_add_f32_e32 v93, 1.0, v93
	v_rcp_f32_e32 v92, v92
	v_rcp_f32_e32 v93, v93
	v_pk_mul_f32 v[84:85], v[84:85], v[90:91]
	s_nop 0
	v_pk_mul_f32 v[80:81], v[84:85], v[80:81]
	v_or_b32_e32 v84, 48, v150
	v_cvt_pk_bf16_f32 v232, v80, v81
	v_pk_mul_f32 v[80:81], v[86:87], v[92:93]
	s_nop 0
	v_pk_mul_f32 v[80:81], v[80:81], v[82:83]
	v_mul_f32_e32 v82, 0xbfb8aa3b, v78
	v_cvt_pk_bf16_f32 v233, v80, v81
	s_nop 0
	v_mul_f32_e32 v80, 0xbfb8aa3b, v76
	v_mul_f32_e32 v81, 0xbfb8aa3b, v77
	v_exp_f32_e32 v80, v80
	v_exp_f32_e32 v81, v81
	v_mul_f32_e32 v83, 0xbfb8aa3b, v79
	v_exp_f32_e32 v82, v82
	v_exp_f32_e32 v83, v83
	v_add_f32_e32 v80, 1.0, v80
	v_add_f32_e32 v81, 1.0, v81
	v_rcp_f32_e32 v80, v80
	v_rcp_f32_e32 v81, v81
	v_add_f32_e32 v82, 1.0, v82
	v_add_f32_e32 v83, 1.0, v83
	v_rcp_f32_e32 v82, v82
	v_rcp_f32_e32 v83, v83
	v_pk_mul_f32 v[76:77], v[76:77], v[80:81]
	s_nop 0
	v_pk_mul_f32 v[72:73], v[76:77], v[72:73]
	v_pk_mul_f32 v[76:77], v[78:79], v[82:83]
	v_cvt_pk_bf16_f32 v234, v72, v73
	v_mul_f32_e32 v73, 0xbfb8aa3b, v68
	v_pk_mul_f32 v[74:75], v[76:77], v[74:75]
	v_exp_f32_e32 v76, v73
	v_mul_f32_e32 v73, 0xbfb8aa3b, v69
	v_exp_f32_e32 v77, v73
	v_cvt_pk_bf16_f32 v235, v74, v75
	v_add_f32_e32 v74, 1.0, v76
	v_mul_f32_e32 v76, 0xbfb8aa3b, v70
	v_add_f32_e32 v75, 1.0, v77
	v_mul_f32_e32 v77, 0xbfb8aa3b, v71
	v_exp_f32_e32 v76, v76
	v_exp_f32_e32 v77, v77
	v_rcp_f32_e32 v74, v74
	v_rcp_f32_e32 v75, v75
	v_add_f32_e32 v76, 1.0, v76
	v_add_f32_e32 v77, 1.0, v77
	v_rcp_f32_e32 v76, v76
	v_rcp_f32_e32 v77, v77
	v_pk_mul_f32 v[68:69], v[68:69], v[74:75]
	s_nop 0
	v_pk_mul_f32 v[64:65], v[68:69], v[64:65]
	v_add_u32_e32 v68, 0x80, v150
	v_cvt_pk_bf16_f32 v236, v64, v65
	v_pk_mul_f32 v[64:65], v[70:71], v[76:77]
	s_nop 0
	v_pk_mul_f32 v[64:65], v[64:65], v[66:67]
	v_mul_f32_e32 v66, 0xbfb8aa3b, v62
	v_cvt_pk_bf16_f32 v237, v64, v65
	s_nop 0
	v_mul_f32_e32 v64, 0xbfb8aa3b, v60
	v_mul_f32_e32 v65, 0xbfb8aa3b, v61
	v_exp_f32_e32 v64, v64
	v_exp_f32_e32 v65, v65
	v_mul_f32_e32 v67, 0xbfb8aa3b, v63
	v_exp_f32_e32 v66, v66
	v_exp_f32_e32 v67, v67
	v_add_f32_e32 v64, 1.0, v64
	v_add_f32_e32 v65, 1.0, v65
	v_rcp_f32_e32 v64, v64
	v_rcp_f32_e32 v65, v65
	v_add_f32_e32 v66, 1.0, v66
	v_add_f32_e32 v67, 1.0, v67
	v_rcp_f32_e32 v66, v66
	v_rcp_f32_e32 v67, v67
	v_pk_mul_f32 v[60:61], v[60:61], v[64:65]
	s_nop 0
	v_pk_mul_f32 v[56:57], v[60:61], v[56:57]
	v_pk_mul_f32 v[60:61], v[62:63], v[66:67]
; __device__ __forceinline__ unsigned pk2(float lo, float hi) { f32x2 v = {lo, hi}; bf16x2_t b = __builtin_convertvector(v, bf16x2_t); return __builtin_bit_cast(unsigned, b); }
; __device__ __forceinline__ float silu_f(float a) { return a * __builtin_amdgcn_rcpf(1.0f + __expf(-a)); }
;     __device__ __forceinline__ void operator()(const f32x4 (&acc)[2][2][4][2], const Unit& u, int wr, int wc, int fr, int fq) const {
;         const int row0 = u.pm * BM + wr * 64 + fr; const int col0 = u.pn * HALF + wc * 32 + 8 * fq;
; #pragma unroll
;         for (int ai = 0; ai < 2; ++ai)
; #pragma unroll
;             for (int m = 0; m < 4; ++m) { const int row = row0 + ai * HALF + m * 16;
;                 const f32x4 a0 = acc[ai][0][m][0], a1 = acc[ai][0][m][1], b0 = acc[ai][1][m][0], b1 = acc[ai][1][m][1];
;                 u32x4 w; w.x = pk2(silu_f(a0[0]) * b0[0], silu_f(a0[1]) * b0[1]); w.y = pk2(silu_f(a0[2]) * b0[2], silu_f(a0[3]) * b0[3]);
;                 w.z = pk2(silu_f(a1[0]) * b1[0], silu_f(a1[1]) * b1[1]); w.w = pk2(silu_f(a1[2]) * b1[2], silu_f(a1[3]) * b1[3]);
;                 *(u32x4*)(H + (size_t)row * ldh + col0) = w; }
	v_cvt_pk_bf16_f32 v238, v56, v57
	v_mul_f32_e32 v57, 0xbfb8aa3b, v52
	v_pk_mul_f32 v[58:59], v[60:61], v[58:59]
	v_exp_f32_e32 v60, v57
	v_mul_f32_e32 v57, 0xbfb8aa3b, v53
	v_exp_f32_e32 v61, v57
	v_cvt_pk_bf16_f32 v239, v58, v59
	v_add_f32_e32 v58, 1.0, v60
	v_mul_f32_e32 v60, 0xbfb8aa3b, v54
	v_add_f32_e32 v59, 1.0, v61
	v_mul_f32_e32 v61, 0xbfb8aa3b, v55
	v_exp_f32_e32 v60, v60
	v_exp_f32_e32 v61, v61
	v_rcp_f32_e32 v58, v58
	v_rcp_f32_e32 v59, v59
	v_add_f32_e32 v60, 1.0, v60
	v_add_f32_e32 v61, 1.0, v61
	v_rcp_f32_e32 v60, v60
	v_rcp_f32_e32 v61, v61
	v_pk_mul_f32 v[52:53], v[52:53], v[58:59]
	s_nop 0
	v_pk_mul_f32 v[48:49], v[52:53], v[48:49]
	v_add_u32_e32 v52, 0x90, v150
	v_cvt_pk_bf16_f32 v240, v48, v49
	v_pk_mul_f32 v[48:49], v[54:55], v[60:61]
	s_nop 0
	v_pk_mul_f32 v[48:49], v[48:49], v[50:51]
	v_mul_f32_e32 v50, 0xbfb8aa3b, v46
	v_cvt_pk_bf16_f32 v241, v48, v49
	s_nop 0
	v_mul_f32_e32 v48, 0xbfb8aa3b, v44
	v_mul_f32_e32 v49, 0xbfb8aa3b, v45
	v_exp_f32_e32 v48, v48
	v_exp_f32_e32 v49, v49
	v_mul_f32_e32 v51, 0xbfb8aa3b, v47
	v_exp_f32_e32 v50, v50
	v_exp_f32_e32 v51, v51
	v_add_f32_e32 v48, 1.0, v48
	v_add_f32_e32 v49, 1.0, v49
	v_rcp_f32_e32 v48, v48
	v_rcp_f32_e32 v49, v49
	v_add_f32_e32 v50, 1.0, v50
	v_add_f32_e32 v51, 1.0, v51
	v_rcp_f32_e32 v50, v50
	v_rcp_f32_e32 v51, v51
	v_pk_mul_f32 v[44:45], v[44:45], v[48:49]
	s_nop 0
	v_pk_mul_f32 v[40:41], v[44:45], v[40:41]
	v_pk_mul_f32 v[44:45], v[46:47], v[50:51]
	v_cvt_pk_bf16_f32 v242, v40, v41
	v_mul_f32_e32 v41, 0xbfb8aa3b, v36
	v_pk_mul_f32 v[42:43], v[44:45], v[42:43]
	v_exp_f32_e32 v44, v41
	v_mul_f32_e32 v41, 0xbfb8aa3b, v37
	v_exp_f32_e32 v45, v41
	v_cvt_pk_bf16_f32 v243, v42, v43
	v_add_f32_e32 v42, 1.0, v44
	v_mul_f32_e32 v44, 0xbfb8aa3b, v38
	v_add_f32_e32 v43, 1.0, v45
	v_mul_f32_e32 v45, 0xbfb8aa3b, v39
	v_exp_f32_e32 v44, v44
	v_exp_f32_e32 v45, v45
	v_rcp_f32_e32 v42, v42
	v_rcp_f32_e32 v43, v43
	v_add_f32_e32 v44, 1.0, v44
	v_add_f32_e32 v45, 1.0, v45
	v_rcp_f32_e32 v44, v44
	v_rcp_f32_e32 v45, v45
	v_pk_mul_f32 v[36:37], v[36:37], v[42:43]
	s_nop 0
	v_pk_mul_f32 v[32:33], v[36:37], v[32:33]
	v_add_u32_e32 v36, 0xa0, v150
	v_cvt_pk_bf16_f32 v244, v32, v33
	v_pk_mul_f32 v[32:33], v[38:39], v[44:45]
	s_nop 0
	v_pk_mul_f32 v[32:33], v[32:33], v[34:35]
	v_mul_f32_e32 v34, 0xbfb8aa3b, v30
	v_cvt_pk_bf16_f32 v245, v32, v33
	s_nop 0
	v_mul_f32_e32 v32, 0xbfb8aa3b, v28
	v_mul_f32_e32 v33, 0xbfb8aa3b, v29
	v_exp_f32_e32 v32, v32
	v_exp_f32_e32 v33, v33
	v_mul_f32_e32 v35, 0xbfb8aa3b, v31
	v_exp_f32_e32 v34, v34
	v_exp_f32_e32 v35, v35
	v_add_f32_e32 v32, 1.0, v32
	v_add_f32_e32 v33, 1.0, v33
	v_rcp_f32_e32 v32, v32
	v_rcp_f32_e32 v33, v33
	v_add_f32_e32 v34, 1.0, v34
	v_add_f32_e32 v35, 1.0, v35
	v_rcp_f32_e32 v34, v34
	v_rcp_f32_e32 v35, v35
	v_pk_mul_f32 v[28:29], v[28:29], v[32:33]
	s_nop 0
	v_pk_mul_f32 v[24:25], v[28:29], v[24:25]
	v_pk_mul_f32 v[28:29], v[30:31], v[34:35]
	v_cvt_pk_bf16_f32 v246, v24, v25
	v_mul_f32_e32 v25, 0xbfb8aa3b, v20
	v_pk_mul_f32 v[26:27], v[28:29], v[26:27]
	v_exp_f32_e32 v28, v25
	v_mul_f32_e32 v25, 0xbfb8aa3b, v21
	v_exp_f32_e32 v29, v25
	v_cvt_pk_bf16_f32 v247, v26, v27
	v_add_f32_e32 v26, 1.0, v28
	v_mul_f32_e32 v28, 0xbfb8aa3b, v22
	v_add_f32_e32 v27, 1.0, v29
	v_mul_f32_e32 v29, 0xbfb8aa3b, v23
	v_exp_f32_e32 v28, v28
	v_exp_f32_e32 v29, v29
	v_rcp_f32_e32 v26, v26
	v_rcp_f32_e32 v27, v27
	v_add_f32_e32 v28, 1.0, v28
	v_add_f32_e32 v29, 1.0, v29
	v_rcp_f32_e32 v28, v28
	v_rcp_f32_e32 v29, v29
	v_pk_mul_f32 v[20:21], v[20:21], v[26:27]
	s_nop 0
	v_pk_mul_f32 v[16:17], v[20:21], v[16:17]
	v_add_u32_e32 v20, 0xb0, v150
	v_cvt_pk_bf16_f32 v248, v16, v17
	v_pk_mul_f32 v[16:17], v[22:23], v[28:29]
	s_nop 0
	v_pk_mul_f32 v[16:17], v[16:17], v[18:19]
	v_mul_f32_e32 v18, 0xbfb8aa3b, v14
	v_cvt_pk_bf16_f32 v249, v16, v17
	s_nop 0
	v_mul_f32_e32 v16, 0xbfb8aa3b, v12
	v_mul_f32_e32 v17, 0xbfb8aa3b, v13
	v_exp_f32_e32 v16, v16
	v_exp_f32_e32 v17, v17
	v_mul_f32_e32 v19, 0xbfb8aa3b, v15
	v_exp_f32_e32 v18, v18
	v_exp_f32_e32 v19, v19
	v_add_f32_e32 v16, 1.0, v16
	v_add_f32_e32 v17, 1.0, v17
	v_rcp_f32_e32 v16, v16
	v_rcp_f32_e32 v17, v17
	v_add_f32_e32 v18, 1.0, v18
	v_add_f32_e32 v19, 1.0, v19
	v_rcp_f32_e32 v18, v18
	v_rcp_f32_e32 v19, v19
	v_pk_mul_f32 v[12:13], v[12:13], v[16:17]
	s_nop 0
	v_pk_mul_f32 v[8:9], v[12:13], v[8:9]
	v_pk_mul_f32 v[12:13], v[14:15], v[18:19]
	v_cvt_pk_bf16_f32 v250, v8, v9
	v_mul_f32_e32 v9, 0xbfb8aa3b, v4
	v_pk_mul_f32 v[10:11], v[12:13], v[10:11]
	v_exp_f32_e32 v12, v9
	v_mul_f32_e32 v9, 0xbfb8aa3b, v5
	v_exp_f32_e32 v13, v9
	v_cvt_pk_bf16_f32 v251, v10, v11
	v_add_f32_e32 v10, 1.0, v12
	v_mul_f32_e32 v12, 0xbfb8aa3b, v6
	v_add_f32_e32 v11, 1.0, v13
	v_mul_f32_e32 v13, 0xbfb8aa3b, v7
	v_exp_f32_e32 v12, v12
	v_exp_f32_e32 v13, v13
	v_rcp_f32_e32 v10, v10
	v_rcp_f32_e32 v11, v11
	v_add_f32_e32 v12, 1.0, v12
	v_add_f32_e32 v13, 1.0, v13
	v_rcp_f32_e32 v12, v12
	v_rcp_f32_e32 v13, v13
	v_pk_mul_f32 v[4:5], v[4:5], v[10:11]
	s_nop 0
	v_pk_mul_f32 v[0:1], v[4:5], v[0:1]
	s_nop 0
	v_cvt_pk_bf16_f32 v252, v0, v1
	v_pk_mul_f32 v[0:1], v[6:7], v[12:13]
	s_nop 0
	v_pk_mul_f32 v[0:1], v[0:1], v[2:3]
	s_nop 0
	v_cvt_pk_bf16_f32 v253, v0, v1
	s_nop 0
	s_mov_b32 s77, 0
	s_cbranch_vccnz .LBB0_1338
	s_andn2_b64 vcc, exec, s[6:7]
	s_cbranch_vccnz .LBB0_1337
	s_barrier
	s_branch .LBB0_1337
